# v12 plus hgrn local lower bound fetched once per block, hgrn out head-norm weights and lower bound fetched once per block and parked in LDS
# speedup vs baseline: 1.0109x; 1.0047x over previous
; #define LAS __attribute__((address_space(3)))
; __device__ __forceinline__ float sigmf(float v) { return __builtin_amdgcn_rcpf(1.0f + __builtin_amdgcn_exp2f(-1.4426950408889634f * v)); }
; template <bool OUT> __device__ __forceinline__ void hgrn_chunk(const PA& a, LAS unsigned char* wb, LAS float* DLk, LAS float* E7k, LAS float* DALLk, int layer, int h, int lane, const HRaw& raw, ...
;     ...
;         const float lb = (layer == 0) ? 0.f : sigmf(a.in[4][256 + h * 64 + lane] - a.in[4][h * 64 + lane]);
; template <bool OUT> __device__ __forceinline__ void hgrn_pair(const PA& a, LAS unsigned char* lds, int layer, int bh, int s, int wave, int lane) {
;     const int half = wave >> 2, wl = wave & 3, c = half ? 63 - s : s, b = bh >> 2, h = bh & 3, item = bh * 64 + c;
;     float* HU = (float*)(a.ws + WS_HU); float* HA = (float*)(a.ws + WS_HA);
;     LAS unsigned char* wb = lds + wave * 12800;
;     LAS float* DLs = (LAS float*)(wb + 11520);
;     LAS float* SBUF = (LAS float*)(lds + 102400 + half * 16384);
;     LAS float* DALL = (LAS float*)(lds + 135168 + half * 2048);
;     int l15 = lane & 15, q = lane >> 4;
;     const size_t rowc0 = (size_t)b * T + (size_t)c * 128 + (size_t)(2 * wl) * 16;
.LBB0_457:
	v_readlane_b32 s2, v253, 7
	v_mov_b32_e32 v141, v234
	v_readlane_b32 s3, v253, 8
	s_andn2_b64 vcc, exec, s[2:3]
	v_readfirstlane_b32 s0, v141
	v_cndmask_b32_e64 v0, 0, 1, s[2:3]
	v_and_b32_e32 v140, 63, v141
	v_cmp_ne_u32_e64 s[74:75], 1, v0
	s_ashr_i32 s36, s0, 6
	s_cbranch_vccnz .LBB0_502
	s_ashr_i32 s0, s0, 8
	s_and_b32 s8, s36, 3
	s_cmp_lt_u32 s36, 4
	s_mul_i32 s1, s36, 0x3200
	v_lshrrev_b32_e32 v1, 3, v140
	v_lshlrev_b32_e32 v0, 3, v140
	s_cselect_b64 s[10:11], -1, 0
	s_add_i32 s9, s1, 0
	s_lshl_b32 s1, s0, 14
	s_lshl_b32 s0, s0, 11
	v_lshl_or_b32 v142, s8, 5, v1
	v_and_b32_e32 v0, 56, v0
	v_mul_u32_u24_e32 v1, 0x48, v1
	s_add_i32 s15, s0, 0
	s_lshl_b32 s0, s8, 1
	v_lshlrev_b32_e32 v3, 1, v0
	v_lshlrev_b32_e32 v1, 1, v1
	v_add3_u32 v143, s9, v3, v1
	v_lshlrev_b32_e32 v1, 1, v140
	s_or_b32 s0, s0, 1
	s_add_i32 s14, s1, 0
	s_add_i32 s15, s15, 0x21000
	v_add_u32_e32 v146, s9, v1
	s_lshl_b32 s12, s0, 4
	s_lshl_b32 s0, s0, 8
	s_add_i32 s14, s14, 0x19000
	s_lshl_b32 s1, s8, 9
	v_mad_u32_u24 v147, v140, 46, v146
	s_movk_i32 s2, 0xffd2
	s_add_i32 s22, s15, s0
	s_lshl_b32 s0, s8, 12
	s_add_i32 s1, s15, s1
	v_and_b32_e32 v2, 15, v141
	v_mad_i32_i24 v148, v140, s2, v147
	v_and_b32_e32 v3, 48, v141
	s_add_i32 s23, s14, s0
	v_add_u32_e32 v149, v148, v1
	v_mul_u32_u24_e32 v1, 44, v140
	v_add_u32_e32 v3, s9, v3
	v_mul_u32_u24_e32 v2, 48, v2
	s_cmp_eq_u32 s8, 3
	v_lshl_add_u32 v150, v140, 2, s1
	v_cmp_gt_u32_e64 s[40:41], 32, v140
	s_mov_b32 s13, s63
	s_cselect_b64 s[20:21], -1, 0
	v_lshlrev_b32_e32 v220, 1, v0
	v_add_u32_e32 v151, v149, v1
	v_add_u32_e32 v152, v3, v2
	v_mov_b32_e32 v176, 0
	s_andn2_b64 vcc, exec, s[4:5]
	s_cbranch_vccnz .Lmy_lb_done
	v_readlane_b32 s2, v253, 12
	v_readlane_b32 s3, v253, 13
	v_readlane_b32 s0, v252, 0
	s_bfe_u32 s0, s0, 0x20005
	v_lshlrev_b32_e32 v178, 2, v140
	v_mov_b32_e32 v179, v221
	v_lshl_or_b32 v178, s0, 8, v178
	global_load_dwordx2 v[182:183], v221, s[2:3]
	s_waitcnt vmcnt(0)
	v_lshl_add_u64 v[182:183], v[182:183], 0, v[178:179]
	flat_load_dword v176, v[182:183] offset:1024
	s_nop 0
	flat_load_dword v178, v[182:183]
	s_waitcnt vmcnt(0) lgkmcnt(0)
	v_sub_f32_e32 v176, v176, v178
	v_mul_f32_e32 v176, 0xbfb8aa3b, v176
	v_exp_f32_e32 v176, v176
	s_nop 0
	v_add_f32_e32 v176, 1.0, v176
	v_rcp_f32_e32 v176, v176
.Lmy_lb_done:
	v_readlane_b32 s30, v252, 0
	s_cmpk_lg_i32 s92, 0x100
	s_cbranch_scc1 .LBB0_460
	s_bitcmp0_b32 s30, 4
	s_cbranch_scc1 .LBB0_502
	s_addk_i32 s30, 0xfff0
	s_branch .LBB0_460

; #define LAS __attribute__((address_space(3)))
; #define LDS_WAIT() asm volatile("s_waitcnt lgkmcnt(0)" ::: "memory")
; __device__ __forceinline__ float sigmf(float v) { return __builtin_amdgcn_rcpf(1.0f + __builtin_amdgcn_exp2f(-1.4426950408889634f * v)); }
; template <bool OUT> __device__ __forceinline__ HRaw hgrn_loadc(const PA& a, int bh, int c, int chunk, int lane) {
;     const bf16* pr = (const bf16*)(a.ws + WS_PROJ) + ((size_t)(bh >> 2) * T + (size_t)c * 128 + chunk * 16 + (lane >> 3)) * DIN + (bh & 3) * 64 + (lane & 7) * 8;
;     HRaw r;
; #pragma unroll
;     for (int k = 0; k < 2; ++k) { r.f[k] = *(const v4u*)(pr + (size_t)(8 * k) * DIN + 256); r.v[k] = *(const v4u*)(pr + (size_t)(8 * k) * DIN + 512);
;         if (OUT) { r.q[k] = *(const v4u*)(pr + (size_t)(8 * k) * DIN); } }
;     return r;
; }
; template <bool OUT> __device__ __forceinline__ void hgrn_chunk(const PA& a, LAS unsigned char* wb, LAS float* DLk, LAS float* E7k, LAS float* DALLk, int layer, int h, int lane, const HRaw& raw, ...
;     LAS bf16* QT = (LAS bf16*)wb; LAS bf16* KT = (LAS bf16*)(wb + 2304); LAS bf16* KHT = (LAS bf16*)(wb + 4608); LAS bf16* VT = (LAS bf16*)(wb + 7680); LAS bf16* P = (LAS bf16*)(wb + 10752);
;     LAS bf16* RF = (LAS bf16*)wb; LAS bf16* RV = (LAS bf16*)(wb + 2304); LAS bf16* RQ = (LAS bf16*)(wb + 4608);
;     const int l15 = lane & 15, q = lane >> 4;
;     const bf16x8 zero8 = {0, 0, 0, 0, 0, 0, 0, 0};
;     LDS_WAIT();
;     {
;         const int rr = lane >> 3, cc = (lane & 7) * 8;
; #pragma unroll
;         for (int k = 0; k < 2; ++k) { *(LAS v4u*)(RF + (rr + 8 * k) * 72 + cc) = raw.f[k]; *(LAS v4u*)(RV + (rr + 8 * k) * 72 + cc) = raw.v[k]; if (OUT) *(LAS v4u*)(RQ + (rr + 8 * k) * 72 + cc) = raw.q[k]; }
;         LDS_WAIT();
;         const float lb = (layer == 0) ? 0.f : sigmf(a.in[4][256 + h * 64 + lane] - a.in[4][h * 64 + lane]);
.LBB0_460:
	s_and_b32 s3, s30, 31
	s_ashr_i32 s2, s30, 5
	s_xor_b32 s24, s3, 63
	s_and_b64 s[0:1], s[10:11], exec
	s_cselect_b32 s31, s3, s24
	s_ashr_i32 s0, s30, 7
	s_ashr_i32 s1, s0, 31
	s_lshl_b64 s[24:25], s[0:1], 13
	s_lshl_b32 s0, s31, 7
	s_or_b32 s24, s24, s0
	v_or_b32_e32 v2, s24, v142
	v_mov_b64_e32 v[0:1], s[60:61]
	s_lshl_b32 s37, s2, 6
	v_mad_u64_u32 v[0:1], s[0:1], v2, s93, v[0:1]
	v_mov_b32_e32 v2, 0x1c00
	s_and_b32 s0, s37, 0xc0
	v_mad_i32_i24 v1, s25, v2, v1
	s_lshl_b32 s62, s0, 1
	v_lshl_add_u64 v[0:1], v[0:1], 0, s[62:63]
	v_lshl_add_u64 v[8:9], v[0:1], 0, v[220:221]
	v_add_co_u32_e32 v12, vcc, s55, v8
	s_nop 1
	v_addc_co_u32_e32 v13, vcc, 0, v9, vcc
	s_barrier
	global_load_dwordx4 v[0:3], v[8:9], off offset:512
	global_load_dwordx4 v[4:7], v[8:9], off offset:1024
	s_nop 0
	global_load_dwordx4 v[8:11], v[12:13], off offset:512
	s_nop 0
	global_load_dwordx4 v[12:15], v[12:13], off offset:1024
	v_ashrrev_i32_e32 v180, 3, v140
	v_mov_b32_e32 v181, s24
	v_or_b32_e32 v181, s12, v181
	v_add_u32_e32 v180, v181, v180
	v_mul_lo_u32 v180, v180, s93
	v_and_b32_e32 v181, 7, v140
	v_lshlrev_b32_e32 v181, 4, v181
	v_add3_u32 v180, v180, v181, s62
	global_load_dwordx4 v[160:163], v180, s[60:61] offset:512
	global_load_dwordx4 v[164:167], v180, s[60:61] offset:1024
	v_add_u32_e32 v181, s55, v180
	global_load_dwordx4 v[168:171], v181, s[60:61] offset:512
	global_load_dwordx4 v[172:175], v181, s[60:61] offset:1024
	s_waitcnt lgkmcnt(0)
	s_and_b32 s38, s2, 3
	s_andn2_b64 vcc, exec, s[4:5]
	s_waitcnt vmcnt(7)
	ds_write_b128 v143, v[0:3]
	s_waitcnt vmcnt(6)
	ds_write_b128 v143, v[4:7] offset:2304
	s_waitcnt vmcnt(5)
	ds_write_b128 v143, v[8:11] offset:1152
	s_waitcnt vmcnt(4)
	ds_write_b128 v143, v[12:15] offset:3456
	s_waitcnt lgkmcnt(0)
	v_cndmask_b32_e64 v1, 0, 1, s[4:5]
	v_mov_b32_e32 v0, 0
	v_cmp_ne_u32_e64 s[0:1], 1, v1
	v_mov_b32_e32 v1, 0
	s_cbranch_vccnz .LBB0_462
	v_mov_b32_e32 v1, v176

; #define LAS __attribute__((address_space(3)))
; __device__ __forceinline__ unsigned pk2(float lo, float hi) { return f2bf(lo) | (f2bf(hi) << 16); }
; template <bool OUT> __device__ __forceinline__ void hgrn_item2(const PA& a, LAS unsigned char* lds, int layer, int bh, int c, int wave, int lane, const HRaw& raw) {
;     const int b = bh >> 2, h = bh & 3, item = bh * 64 + c;
;     float* HU = (float*)(a.ws + WS_HU); float* HA = (float*)(a.ws + WS_HA);
;     LAS unsigned char* wb = lds + wave * 12288;
;     LAS bf16* QT = (LAS bf16*)wb; LAS bf16* KT = (LAS bf16*)(wb + 2304); LAS bf16* KHT = (LAS bf16*)(wb + 4608); LAS bf16* VT = (LAS bf16*)(wb + 7680); LAS bf16* P = (LAS bf16*)(wb + 10752);
;     LAS float* DL = (LAS float*)(wb + 11520); LAS float* E7L = (LAS float*)(wb + 11776);
;     LAS bf16* RF = (LAS bf16*)wb; LAS bf16* RV = (LAS bf16*)(wb + 2304); LAS bf16* RQ = (LAS bf16*)(wb + 4608);
;     LAS bf16* GT = KHT; LAS bf16* OT = VT;
;     LAS float* SBUF = (LAS float*)(lds + 98304); LAS float* DALL = (LAS float*)(lds + 114688);
;     const int l15 = lane & 15, q = lane >> 4;
;     const size_t row0 = (size_t)b * T + (size_t)c * 128 + wave * 16;
;     const bf16x8 zero8 = {0, 0, 0, 0, 0, 0, 0, 0};
;     ...
;         for (int mt = 0; mt < 4; ++mt) { const f32x4 Ev = *(const LAS f32x4*)(E7L + 16 * mt + 4 * q);
; #pragma unroll
;             for (int nt = 0; nt < 4; ++nt) Sp[mt][nt] = Sp[mt][nt] * Ev; }
; #pragma unroll
;         for (int nt = 0; nt < 4; ++nt)
; #pragma unroll
;             for (int ks = 0; ks < 2; ++ks) {
;                 const f32x4 s0 = Sp[2 * ks][nt], s1 = Sp[2 * ks + 1][nt];
;                 const bf16x8 bfrag = __builtin_bit_cast(bf16x8, (v4u){pk2(s0[0], s0[1]), pk2(s0[2], s0[3]), pk2(s1[0], s1[1]), pk2(s1[2], s1[3])});
;                 o[nt] = __builtin_amdgcn_mfma_f32_16x16x32_bf16(qf[ks], bfrag, o[nt], 0, 0, 0);
;             }
.LBB0_705:
	v_readlane_b32 s0, v253, 7
	v_mov_b32_e32 v0, v234
	v_readlane_b32 s1, v253, 8
	s_andn2_b64 vcc, exec, s[0:1]
	v_readfirstlane_b32 s0, v0
	s_cbranch_vccnz .LBB0_756
	s_ashr_i32 s2, s0, 6
	s_lshl_b32 s0, s2, 4
	v_bfe_u32 v1, v0, 3, 3
	v_and_b32_e32 v200, 63, v0
	s_ashr_i32 s1, s0, 31
	v_or_b32_e32 v188, s0, v1
	v_lshlrev_b32_e32 v2, 3, v0
	s_mul_i32 s0, s2, 0x3000
	v_and_b32_e32 v2, 56, v2
	s_add_i32 s3, s0, 0
	v_mul_u32_u24_e32 v1, 0x48, v1
	v_lshlrev_b32_e32 v5, 1, v200
	v_lshlrev_b32_e32 v4, 1, v2
	v_lshlrev_b32_e32 v1, 1, v1
	v_add_u32_e32 v202, s3, v5
	v_add3_u32 v201, s3, v4, v1
	v_add_u32_e32 v203, v202, v5
	v_or_b32_e32 v5, 16, v200
	v_add3_u32 v204, s3, v1, v4
	v_bfe_u32 v4, v0, 2, 4
	v_mul_u32_u24_e32 v12, 48, v5
	v_or_b32_e32 v5, 48, v200
	v_and_b32_e32 v14, 12, v4
	v_and_b32_e32 v3, 15, v0
	v_mul_u32_u24_e32 v13, 48, v5
	v_or_b32_e32 v5, 1, v14
	v_mul_u32_u24_e32 v1, 0x48, v3
	v_cmp_gt_u32_e64 s[42:43], v3, v5
	v_or_b32_e32 v5, 2, v14
	v_or_b32_e32 v16, 3, v4
	v_lshl_or_b32 v4, s2, 7, v200
	v_lshl_add_u32 v1, v1, 1, s3
	s_movk_i32 s0, 0xff72
	v_cmp_gt_u32_e64 s[44:45], v3, v5
	v_ashrrev_i32_e32 v5, 31, v4
	v_lshl_add_u32 v205, v14, 1, v1
	v_mad_i32_i24 v1, v3, s0, v1
	v_lshlrev_b64 v[224:225], 4, v[4:5]
	v_or_b32_e32 v6, 64, v4
	v_lshlrev_b32_e32 v206, 4, v4
	v_readlane_b32 s0, v254, 44
	v_mul_u32_u24_e32 v4, 0x48, v14
	v_or_b32_e32 v4, v4, v3
	v_lshl_or_b32 v194, s0, 6, v3
	s_movk_i32 s0, 0x48
	v_lshl_add_u32 v209, v4, 1, s3
	v_mad_u32_u24 v4, v14, s0, s0
	v_mul_u32_u24_e32 v11, 48, v3
	v_cmp_gt_u32_e64 s[40:41], v3, v14
	v_cmp_gt_u32_e64 s[46:47], v3, v16
	v_mad_u32_u24 v18, v3, 48, s3
	v_add_u32_e32 v3, v4, v3
	v_and_b32_e32 v9, 16, v0
	v_lshl_add_u32 v3, v3, 1, s3
	v_mul_u32_u24_e32 v8, 44, v200
	v_add_u32_e32 v10, s3, v9
	v_mul_u32_u24_e32 v15, 48, v14
	v_mul_u32_u24_e32 v17, 48, v16
	v_ashrrev_i32_e32 v7, 31, v6
	v_and_b32_e32 v208, 48, v0
	v_lshlrev_b32_e32 v0, 4, v200
	v_add_u32_e32 v211, 0x90, v3
	v_mul_u32_u24_e32 v3, 0x48, v16
	v_mov_b32_e32 v189, s1
	v_cmp_gt_u32_e64 s[38:39], 32, v200
	v_lshlrev_b64 v[240:241], 4, v[6:7]
	v_lshlrev_b32_e32 v207, 4, v6
	v_mov_b32_e32 v195, v221
	v_lshl_add_u32 v210, v4, 1, v1
	v_lshl_add_u32 v212, v3, 1, v1
	v_lshlrev_b32_e32 v220, 1, v2
	v_add_u32_e32 v213, v203, v8
	v_add_u32_e32 v214, v10, v11
	v_add_u32_e32 v215, v10, v12
	v_add_u32_e32 v216, v10, v13
	v_add_u32_e32 v217, v1, v15
	v_add_u32_e32 v218, v1, v17
	v_add_u32_e32 v219, v18, v9
	v_add_u32_e32 v226, 0, v0
	v_readlane_b32 s0, v253, 29
	v_readlane_b32 s1, v253, 30
	v_readlane_b32 s14, v253, 12
	v_readlane_b32 s15, v253, 13
	v_readlane_b32 s8, v252, 0
	s_bfe_u32 s8, s8, 0x20005
	v_lshlrev_b32_e32 v24, 2, v200
	v_lshl_or_b32 v24, s8, 8, v24
	v_mov_b32_e32 v25, v221
	global_load_dwordx2 v[20:21], v221, s[0:1]
	global_load_dwordx2 v[22:23], v221, s[14:15]
	s_waitcnt vmcnt(0)
	v_lshl_add_u64 v[20:21], v[194:195], 2, v[20:21]
	v_lshl_add_u64 v[22:23], v[22:23], 0, v[24:25]
	flat_load_dword v28, v[20:21]
	flat_load_dword v29, v[20:21] offset:64
	flat_load_dword v27, v[20:21] offset:128
	flat_load_dword v26, v[20:21] offset:192
	v_mov_b32_e32 v30, 0
	s_andn2_b64 vcc, exec, s[4:5]
	s_cbranch_vccnz .Lmy_ho_nolb
	flat_load_dword v30, v[22:23] offset:1024
	s_nop 0
	flat_load_dword v31, v[22:23]
	s_waitcnt vmcnt(0) lgkmcnt(0)
	v_sub_f32_e32 v30, v30, v31
	v_mul_f32_e32 v30, 0xbfb8aa3b, v30
	v_exp_f32_e32 v30, v30
	s_nop 0
	v_add_f32_e32 v30, 1.0, v30
	v_rcp_f32_e32 v30, v30
.Lmy_ho_nolb:
	s_waitcnt vmcnt(0) lgkmcnt(0)
	v_lshlrev_b32_e32 v31, 5, v234
	v_add_u32_e32 v31, 0x1e000, v31
	ds_write_b128 v31, v[26:29]
	ds_write_b32 v31, v30 offset:16
	v_readlane_b32 s8, v252, 0
	s_branch .LBB0_708
.LBB0_707:
	ds_read_b128 v[32:35], v251 offset:11776
	ds_read_b128 v[48:51], v251 offset:11904
	v_mfma_f32_16x16x32_bf16 v[12:15], v[72:75], v[12:15], 0
	v_readlane_b32 s0, v253, 29
	v_readlane_b32 s1, v253, 30
	s_waitcnt lgkmcnt(1)
	v_pk_mul_f32 v[52:53], v[106:107], v[34:35]
	v_pk_mul_f32 v[40:41], v[122:123], v[34:35]
	v_pk_mul_f32 v[28:29], v[138:139], v[34:35]
	v_pk_mul_f32 v[24:25], v[150:151], v[34:35]
	ds_read_b128 v[34:37], v251 offset:11840
	v_mfma_f32_16x16x32_bf16 v[20:23], v[72:75], v[20:23], 0
	v_mul_f32_e64 v54, v104, v32
	v_mul_f32_e64 v55, v105, v33
	v_pk_mul_f32 v[42:43], v[120:121], v[32:33]
	v_pk_mul_f32 v[30:31], v[136:137], v[32:33]
	v_pk_mul_f32 v[26:27], v[148:149], v[32:33]
	s_waitcnt lgkmcnt(0)
	v_pk_mul_f32 v[56:57], v[102:103], v[36:37]
	v_pk_mul_f32 v[60:61], v[94:95], v[36:37]
	v_pk_mul_f32 v[44:45], v[114:115], v[36:37]
	v_pk_mul_f32 v[32:33], v[130:131], v[36:37]
	v_pk_mul_f32 v[64:65], v[126:127], v[50:51]
	v_pk_mul_f32 v[66:67], v[124:125], v[48:49]
	v_pk_mul_f32 v[68:69], v[142:143], v[50:51]
	v_pk_mul_f32 v[70:71], v[140:141], v[48:49]
	v_pk_mul_f32 v[72:73], v[146:147], v[50:51]
	v_pk_mul_f32 v[74:75], v[144:145], v[48:49]
	v_pk_mul_f32 v[36:37], v[154:155], v[50:51]
	v_pk_mul_f32 v[38:39], v[152:153], v[48:49]
	ds_read_b128 v[48:51], v251 offset:11968
	v_pk_mul_f32 v[58:59], v[100:101], v[34:35]
	v_pk_mul_f32 v[62:63], v[92:93], v[34:35]
	v_pk_mul_f32 v[46:47], v[112:113], v[34:35]
	v_pk_mul_f32 v[34:35], v[128:129], v[34:35]
	s_waitcnt lgkmcnt(0)
; __device__ __forceinline__ unsigned pk2(float lo, float hi) { return f2bf(lo) | (f2bf(hi) << 16); }
; template <bool OUT> __device__ __forceinline__ void hgrn_item2(const PA& a, LAS unsigned char* lds, int layer, int bh, int c, int wave, int lane, const HRaw& raw) {
;     ...
; #pragma unroll
;         for (int nt = 0; nt < 4; ++nt)
; #pragma unroll
;             for (int ks = 0; ks < 2; ++ks) {
;                 const f32x4 s0 = Sp[2 * ks][nt], s1 = Sp[2 * ks + 1][nt];
;                 const bf16x8 bfrag = __builtin_bit_cast(bf16x8, (v4u){pk2(s0[0], s0[1]), pk2(s0[2], s0[3]), pk2(s1[0], s1[1]), pk2(s1[2], s1[3])});
;                 o[nt] = __builtin_amdgcn_mfma_f32_16x16x32_bf16(qf[ks], bfrag, o[nt], 0, 0, 0);
;             }
	v_pk_mul_f32 v[78:79], v[108:109], v[48:49]
	v_pk_mul_f32 v[82:83], v[96:97], v[48:49]
	v_pk_mul_f32 v[86:87], v[116:117], v[48:49]
	v_pk_mul_f32 v[90:91], v[132:133], v[48:49]
	v_bfe_u32 v48, v54, 16, 1
	v_add3_u32 v48, v54, v48, s73
	v_bfe_u32 v49, v55, 16, 1
	v_lshrrev_b32_e32 v48, 16, v48
	v_add3_u32 v49, v55, v49, s73
	v_and_or_b32 v48, v49, s26, v48
	v_bfe_u32 v49, v52, 16, 1
	v_pk_mul_f32 v[76:77], v[110:111], v[50:51]
	v_pk_mul_f32 v[80:81], v[98:99], v[50:51]
	v_pk_mul_f32 v[84:85], v[118:119], v[50:51]
	v_pk_mul_f32 v[88:89], v[134:135], v[50:51]
	v_add3_u32 v49, v52, v49, s73
	v_bfe_u32 v50, v53, 16, 1
	v_lshrrev_b32_e32 v49, 16, v49
	v_add3_u32 v50, v53, v50, s73
	v_and_or_b32 v49, v50, s26, v49
	v_bfe_u32 v50, v58, 16, 1
	v_add3_u32 v50, v58, v50, s73
	v_bfe_u32 v51, v59, 16, 1
	v_lshrrev_b32_e32 v50, 16, v50
	v_add3_u32 v51, v59, v51, s73
	v_and_or_b32 v50, v51, s26, v50
	v_bfe_u32 v51, v56, 16, 1
	v_add3_u32 v51, v56, v51, s73
	v_bfe_u32 v52, v57, 16, 1
	v_lshrrev_b32_e32 v51, 16, v51
	v_add3_u32 v52, v57, v52, s73
	v_and_or_b32 v51, v52, s26, v51
	v_bfe_u32 v52, v77, 16, 1
	v_add3_u32 v52, v77, v52, s73
	v_mfma_f32_16x16x32_bf16 v[8:11], v[16:19], v[48:51], v[8:11]
	v_bfe_u32 v48, v66, 16, 1
	v_add3_u32 v48, v66, v48, s73
	v_bfe_u32 v49, v67, 16, 1
	v_lshrrev_b32_e32 v48, 16, v48
	v_add3_u32 v49, v67, v49, s73
	v_and_or_b32 v48, v49, s26, v48
	v_bfe_u32 v49, v64, 16, 1
	v_add3_u32 v49, v64, v49, s73
	v_bfe_u32 v50, v65, 16, 1
	v_lshrrev_b32_e32 v49, 16, v49
	v_add3_u32 v50, v65, v50, s73
	v_and_or_b32 v49, v50, s26, v49
	v_bfe_u32 v50, v78, 16, 1
	v_add3_u32 v50, v78, v50, s73
	v_bfe_u32 v51, v79, 16, 1
	v_lshrrev_b32_e32 v50, 16, v50
	v_add3_u32 v51, v79, v51, s73
	v_and_or_b32 v50, v51, s26, v50
	v_bfe_u32 v51, v76, 16, 1
	v_add3_u32 v51, v76, v51, s73
	v_lshrrev_b32_e32 v51, 16, v51
	v_and_or_b32 v51, v52, s26, v51
	s_lshl_b32 s62, s12, 1
	s_add_i32 s8, s8, s92
	v_mfma_f32_16x16x32_bf16 v[8:11], v[0:3], v[48:51], v[8:11]
	v_bfe_u32 v48, v42, 16, 1
	v_add3_u32 v42, v42, v48, s73
	v_bfe_u32 v48, v43, 16, 1
	v_lshrrev_b32_e32 v42, 16, v42
	v_add3_u32 v43, v43, v48, s73
	v_and_or_b32 v48, v43, s26, v42
	v_bfe_u32 v42, v40, 16, 1
	v_add3_u32 v40, v40, v42, s73
	v_bfe_u32 v42, v41, 16, 1
	v_lshrrev_b32_e32 v40, 16, v40
	v_add3_u32 v41, v41, v42, s73
	v_and_or_b32 v49, v41, s26, v40
	v_bfe_u32 v40, v62, 16, 1
	v_add3_u32 v40, v62, v40, s73
	v_bfe_u32 v41, v63, 16, 1
	v_lshrrev_b32_e32 v40, 16, v40
	v_add3_u32 v41, v63, v41, s73
	v_and_or_b32 v50, v41, s26, v40
	v_bfe_u32 v40, v60, 16, 1
	v_add3_u32 v40, v60, v40, s73
	v_bfe_u32 v41, v61, 16, 1
	v_lshrrev_b32_e32 v40, 16, v40
	v_add3_u32 v41, v61, v41, s73
	v_and_or_b32 v51, v41, s26, v40
	v_bfe_u32 v40, v70, 16, 1
	v_add3_u32 v40, v70, v40, s73
	v_bfe_u32 v41, v71, 16, 1
	v_lshrrev_b32_e32 v40, 16, v40
	v_add3_u32 v41, v71, v41, s73
	v_and_or_b32 v40, v41, s26, v40
	v_bfe_u32 v41, v68, 16, 1
	v_add3_u32 v41, v68, v41, s73
	v_bfe_u32 v42, v69, 16, 1
	v_lshrrev_b32_e32 v41, 16, v41
	v_add3_u32 v42, v69, v42, s73
	v_and_or_b32 v41, v42, s26, v41
	v_bfe_u32 v42, v82, 16, 1
	v_add3_u32 v42, v82, v42, s73
	v_bfe_u32 v43, v83, 16, 1
	v_lshrrev_b32_e32 v42, 16, v42
	v_add3_u32 v43, v83, v43, s73
	v_mfma_f32_16x16x32_bf16 v[12:15], v[16:19], v[48:51], v[12:15]
	v_and_or_b32 v42, v43, s26, v42
	v_bfe_u32 v43, v80, 16, 1
	v_add3_u32 v43, v80, v43, s73
	v_bfe_u32 v48, v81, 16, 1
	v_lshrrev_b32_e32 v43, 16, v43
	v_add3_u32 v48, v81, v48, s73
	v_and_or_b32 v43, v48, s26, v43
	s_cmpk_gt_i32 s8, 0xff
	s_nop 0
	v_mfma_f32_16x16x32_bf16 v[12:15], v[0:3], v[40:43], v[12:15]
	v_bfe_u32 v40, v30, 16, 1
	v_add3_u32 v30, v30, v40, s73
	v_bfe_u32 v40, v31, 16, 1
	v_lshrrev_b32_e32 v30, 16, v30
	v_add3_u32 v31, v31, v40, s73
	v_and_or_b32 v40, v31, s26, v30
	v_bfe_u32 v30, v28, 16, 1
	v_add3_u32 v28, v28, v30, s73
	v_bfe_u32 v30, v29, 16, 1
	v_lshrrev_b32_e32 v28, 16, v28
	v_add3_u32 v29, v29, v30, s73
	v_and_or_b32 v41, v29, s26, v28
	v_bfe_u32 v28, v46, 16, 1
	v_add3_u32 v28, v46, v28, s73
	v_bfe_u32 v29, v47, 16, 1
	v_lshrrev_b32_e32 v28, 16, v28
	v_add3_u32 v29, v47, v29, s73
	v_and_or_b32 v42, v29, s26, v28
	v_bfe_u32 v28, v44, 16, 1
	v_add3_u32 v28, v44, v28, s73
	v_bfe_u32 v29, v45, 16, 1
	v_lshrrev_b32_e32 v28, 16, v28
	v_add3_u32 v29, v45, v29, s73
	v_and_or_b32 v43, v29, s26, v28
	v_bfe_u32 v28, v74, 16, 1
	v_add3_u32 v28, v74, v28, s73
	v_bfe_u32 v29, v75, 16, 1
	v_lshrrev_b32_e32 v28, 16, v28
	v_add3_u32 v29, v75, v29, s73
	v_and_or_b32 v28, v29, s26, v28
	v_bfe_u32 v29, v72, 16, 1
	v_add3_u32 v29, v72, v29, s73
	v_bfe_u32 v30, v73, 16, 1
	v_lshrrev_b32_e32 v29, 16, v29
	v_add3_u32 v30, v73, v30, s73
	v_and_or_b32 v29, v30, s26, v29
	v_bfe_u32 v30, v86, 16, 1
	v_add3_u32 v30, v86, v30, s73
	v_bfe_u32 v31, v87, 16, 1
	v_lshrrev_b32_e32 v30, 16, v30
	v_add3_u32 v31, v87, v31, s73
	v_mfma_f32_16x16x32_bf16 v[4:7], v[16:19], v[40:43], v[4:7]
	v_and_or_b32 v30, v31, s26, v30
	v_bfe_u32 v31, v84, 16, 1
	v_add3_u32 v31, v84, v31, s73
	v_bfe_u32 v40, v85, 16, 1
	v_lshrrev_b32_e32 v31, 16, v31
	v_add3_u32 v40, v85, v40, s73
	v_and_or_b32 v31, v40, s26, v31
	s_nop 1
	v_mfma_f32_16x16x32_bf16 v[4:7], v[0:3], v[28:31], v[4:7]
	v_bfe_u32 v28, v26, 16, 1
	v_add3_u32 v26, v26, v28, s73
	v_bfe_u32 v28, v27, 16, 1
	v_lshrrev_b32_e32 v26, 16, v26
	v_add3_u32 v27, v27, v28, s73
	v_and_or_b32 v26, v27, s26, v26
	v_bfe_u32 v27, v24, 16, 1
	v_add3_u32 v24, v24, v27, s73
	v_bfe_u32 v27, v25, 16, 1
	v_lshrrev_b32_e32 v24, 16, v24
	v_add3_u32 v25, v25, v27, s73
	v_and_or_b32 v27, v25, s26, v24
	v_bfe_u32 v24, v34, 16, 1
	v_add3_u32 v24, v34, v24, s73
	v_bfe_u32 v25, v35, 16, 1
	v_lshrrev_b32_e32 v24, 16, v24
; __device__ __forceinline__ unsigned f2bf(float f) { unsigned u = __builtin_bit_cast(unsigned, f); return (u + 0x7fffu + ((u >> 16) & 1u)) >> 16; }
; __device__ __forceinline__ float bf1(bf16 h) { return __uint_as_float(((unsigned)h) << 16); }
; __device__ __forceinline__ float siluf(float v) { return v * sigmf(v); }
; template <bool OUT> __device__ __forceinline__ void hgrn_item2(const PA& a, LAS unsigned char* lds, int layer, int bh, int c, int wave, int lane, const HRaw& raw) {
;     ...
;         float gn[4];
; #pragma unroll
;         for (int nt = 0; nt < 4; ++nt) gn[nt] = a.in[5][layer * 64 + 16 * nt + l15];
; #pragma unroll
;         for (int j = 0; j < 4; ++j) {
;             float ss = (o[0][j] * o[0][j] + o[1][j] * o[1][j]) + (o[2][j] * o[2][j] + o[3][j] * o[3][j]);
;             ss += __shfl_xor(ss, 1); ss += __shfl_xor(ss, 2); ss += __shfl_xor(ss, 4); ss += __shfl_xor(ss, 8);
;             const float rs = __builtin_amdgcn_rsqf(ss * (1.f / 64.f) + EPS);
; #pragma unroll
;             for (int nt = 0; nt < 4; ++nt) { const float gt = siluf(bf1(GT[(4 * q + j) * 72 + 16 * nt + l15]));
;                 OT[(4 * q + j) * 72 + 16 * nt + l15] = (bf16)f2bf(o[nt][j] * rs * gn[nt] * gt); }
	v_add3_u32 v25, v35, v25, s73
	v_and_or_b32 v28, v25, s26, v24
	v_bfe_u32 v24, v32, 16, 1
	v_add3_u32 v24, v32, v24, s73
	v_bfe_u32 v25, v33, 16, 1
	v_lshrrev_b32_e32 v24, 16, v24
	v_add3_u32 v25, v33, v25, s73
	v_and_or_b32 v29, v25, s26, v24
	v_bfe_u32 v24, v89, 16, 1
	v_add3_u32 v24, v89, v24, s73
	v_mfma_f32_16x16x32_bf16 v[16:19], v[16:19], v[26:29], v[20:23]
	s_nop 2
	v_bfe_u32 v20, v38, 16, 1
	v_add3_u32 v20, v38, v20, s73
	v_bfe_u32 v21, v39, 16, 1
	v_lshrrev_b32_e32 v20, 16, v20
	v_add3_u32 v21, v39, v21, s73
	v_and_or_b32 v20, v21, s26, v20
	v_bfe_u32 v21, v36, 16, 1
	v_add3_u32 v21, v36, v21, s73
	v_bfe_u32 v22, v37, 16, 1
	v_lshrrev_b32_e32 v21, 16, v21
	v_add3_u32 v22, v37, v22, s73
	v_and_or_b32 v21, v22, s26, v21
	v_bfe_u32 v22, v90, 16, 1
	v_add3_u32 v22, v90, v22, s73
	v_bfe_u32 v23, v91, 16, 1
	v_lshrrev_b32_e32 v22, 16, v22
	v_add3_u32 v23, v91, v23, s73
	v_and_or_b32 v22, v23, s26, v22
	v_bfe_u32 v23, v88, 16, 1
	v_add3_u32 v23, v88, v23, s73
	v_lshrrev_b32_e32 v23, 16, v23
	v_and_or_b32 v23, v24, s26, v23
	s_nop 1
	v_mfma_f32_16x16x32_bf16 v[0:3], v[0:3], v[20:23], v[16:19]
	s_nop 2
	v_lshlrev_b32_e32 v16, 5, v234
	v_add_u32_e32 v16, 0x1e000, v16
	ds_read_b128 v[16:19], v16
	s_nop 3
	v_mul_f32_e32 v20, v12, v12
	v_mul_f32_e32 v21, v0, v0
	v_fmac_f32_e32 v20, v8, v8
	v_fmac_f32_e32 v21, v4, v4
	v_add_f32_e32 v20, v20, v21
	ds_bpermute_b32 v21, v159, v20
	s_waitcnt lgkmcnt(0)
	v_add_f32_e32 v20, v20, v21
	ds_bpermute_b32 v21, v158, v20
	s_waitcnt lgkmcnt(0)
	v_add_f32_e32 v20, v20, v21
	ds_bpermute_b32 v21, v156, v20
	s_waitcnt lgkmcnt(0)
	v_add_f32_e32 v20, v20, v21
	ds_bpermute_b32 v21, v157, v20
	s_waitcnt lgkmcnt(0)
	v_add_f32_e32 v20, v20, v21
	ds_read_u16 v21, v209 offset:4608
	ds_read_u16 v22, v209 offset:4640
	v_fmamk_f32 v20, v20, 0x3c800000, v235
	v_rsq_f32_e32 v20, v20
	s_waitcnt lgkmcnt(0)
	v_lshlrev_b32_e32 v21, 16, v21
	v_mul_f32_e32 v23, 0xbfb8aa3b, v21
	v_exp_f32_e32 v23, v23
	v_mul_f32_e32 v8, v8, v20
	v_mul_f32_e32 v12, v12, v20
	v_mul_f32_e32 v4, v4, v20
	v_add_f32_e32 v23, 1.0, v23
	v_rcp_f32_e32 v23, v23
	v_mul_f32_e32 v0, v0, v20
	v_mul_f32_e32 v21, v23, v21
	s_waitcnt vmcnt(0) lgkmcnt(0)
	v_mul_f32_e32 v8, v18, v8
	v_mul_f32_e32 v8, v8, v21
	v_bfe_u32 v21, v8, 16, 1
	v_add3_u32 v8, v8, v21, s73
	ds_write_b16_d16_hi v209, v8 offset:7680
	v_lshlrev_b32_e32 v8, 16, v22
	v_mul_f32_e32 v21, 0xbfb8aa3b, v8
	v_exp_f32_e32 v21, v21
	v_mul_f32_e32 v12, v19, v12
	v_mul_f32_e32 v4, v17, v4
	v_mul_f32_e32 v0, v16, v0
	v_add_f32_e32 v21, 1.0, v21
	v_rcp_f32_e32 v21, v21
	s_nop 0
	v_mul_f32_e32 v8, v21, v8
	v_mul_f32_e32 v8, v12, v8
	v_bfe_u32 v12, v8, 16, 1
	v_add3_u32 v8, v8, v12, s73
	ds_write_b16_d16_hi v209, v8 offset:7712
	ds_read_u16 v8, v209 offset:4672
	s_waitcnt lgkmcnt(0)
	v_lshlrev_b32_e32 v8, 16, v8
	v_mul_f32_e32 v12, 0xbfb8aa3b, v8
	v_exp_f32_e32 v12, v12
	s_nop 0
	v_add_f32_e32 v12, 1.0, v12
	v_rcp_f32_e32 v12, v12
	s_nop 0
	v_mul_f32_e32 v8, v12, v8
	v_mul_f32_e32 v4, v4, v8
	v_bfe_u32 v8, v4, 16, 1
	v_add3_u32 v4, v4, v8, s73
	ds_write_b16_d16_hi v209, v4 offset:7744
	ds_read_u16 v4, v209 offset:4704
	s_waitcnt lgkmcnt(0)
	v_lshlrev_b32_e32 v4, 16, v4
	v_mul_f32_e32 v8, 0xbfb8aa3b, v4
	v_exp_f32_e32 v8, v8
	s_nop 0
	v_add_f32_e32 v8, 1.0, v8
	v_rcp_f32_e32 v8, v8
	s_nop 0
	v_mul_f32_e32 v4, v8, v4
	v_mul_f32_e32 v0, v0, v4
	v_bfe_u32 v4, v0, 16, 1
	v_add3_u32 v0, v0, v4, s73
	ds_write_b16_d16_hi v209, v0 offset:7776
	v_mul_f32_e32 v0, v13, v13
	v_mul_f32_e32 v4, v1, v1
	v_fmac_f32_e32 v0, v9, v9
	v_fmac_f32_e32 v4, v5, v5
	v_add_f32_e32 v0, v0, v4
	ds_bpermute_b32 v4, v159, v0
	s_waitcnt lgkmcnt(0)
	v_add_f32_e32 v0, v0, v4
	ds_bpermute_b32 v4, v158, v0
	s_waitcnt lgkmcnt(0)
	v_add_f32_e32 v0, v0, v4
	ds_bpermute_b32 v4, v156, v0
	s_waitcnt lgkmcnt(0)
	v_add_f32_e32 v0, v0, v4
	ds_bpermute_b32 v4, v157, v0
	s_waitcnt lgkmcnt(0)
	v_add_f32_e32 v0, v0, v4
	ds_read_u16 v4, v210 offset:4608
	ds_read_u16 v8, v210 offset:4640
	v_fmamk_f32 v0, v0, 0x3c800000, v235
	v_rsq_f32_e32 v0, v0
	s_waitcnt lgkmcnt(1)
	v_lshlrev_b32_e32 v4, 16, v4
	v_mul_f32_e32 v12, 0xbfb8aa3b, v4
	v_exp_f32_e32 v12, v12
	v_mul_f32_e32 v9, v9, v0
	v_mul_f32_e32 v9, v18, v9
	v_mul_f32_e32 v5, v5, v0
	v_add_f32_e32 v12, 1.0, v12
	v_rcp_f32_e32 v12, v12
	v_mul_f32_e32 v5, v17, v5
	v_mul_f32_e32 v4, v12, v4
	v_mul_f32_e32 v4, v9, v4
	v_bfe_u32 v9, v4, 16, 1
	v_add3_u32 v4, v4, v9, s73
	ds_write_b16_d16_hi v210, v4 offset:7680
	s_waitcnt lgkmcnt(1)
	v_lshlrev_b32_e32 v4, 16, v8
	v_mul_f32_e32 v8, 0xbfb8aa3b, v4
	v_exp_f32_e32 v8, v8
	s_nop 0
	v_add_f32_e32 v8, 1.0, v8
	v_rcp_f32_e32 v8, v8
	s_nop 0
	v_mul_f32_e32 v4, v8, v4
	v_mul_f32_e32 v8, v13, v0
	v_mul_f32_e32 v8, v19, v8
	v_mul_f32_e32 v4, v8, v4
	v_bfe_u32 v8, v4, 16, 1
	v_add3_u32 v4, v4, v8, s73
	ds_write_b16_d16_hi v210, v4 offset:7712
	ds_read_u16 v4, v210 offset:4672
	v_mul_f32_e32 v0, v1, v0
	v_mul_f32_e32 v0, v16, v0
	s_waitcnt lgkmcnt(0)
	v_lshlrev_b32_e32 v4, 16, v4
	v_mul_f32_e32 v8, 0xbfb8aa3b, v4
	v_exp_f32_e32 v8, v8
	s_nop 0
	v_add_f32_e32 v8, 1.0, v8
	v_rcp_f32_e32 v8, v8
	s_nop 0
	v_mul_f32_e32 v4, v8, v4
	v_mul_f32_e32 v4, v5, v4
	v_bfe_u32 v5, v4, 16, 1
	v_add3_u32 v4, v4, v5, s73
	ds_write_b16_d16_hi v210, v4 offset:7744
	ds_read_u16 v4, v210 offset:4704
	s_waitcnt lgkmcnt(0)
	v_lshlrev_b32_e32 v4, 16, v4
	v_mul_f32_e32 v5, 0xbfb8aa3b, v4
	v_exp_f32_e32 v5, v5
	s_nop 0
	v_add_f32_e32 v5, 1.0, v5
	v_rcp_f32_e32 v5, v5
	s_nop 0
	v_mul_f32_e32 v4, v5, v4
	v_mul_f32_e32 v0, v0, v4
	v_bfe_u32 v1, v0, 16, 1
	v_add3_u32 v0, v0, v1, s73
	ds_write_b16_d16_hi v210, v0 offset:7776
	v_mul_f32_e32 v0, v14, v14
	v_mul_f32_e32 v1, v2, v2
	v_fmac_f32_e32 v0, v10, v10
	v_fmac_f32_e32 v1, v6, v6
	v_add_f32_e32 v0, v0, v1
	ds_bpermute_b32 v1, v159, v0
	s_waitcnt lgkmcnt(0)
; #define LAS __attribute__((address_space(3)))
; #define LDS_WAIT() asm volatile("s_waitcnt lgkmcnt(0)" ::: "memory")
; __device__ __forceinline__ unsigned f2bf(float f) { unsigned u = __builtin_bit_cast(unsigned, f); return (u + 0x7fffu + ((u >> 16) & 1u)) >> 16; }
; __device__ __forceinline__ float bf1(bf16 h) { return __uint_as_float(((unsigned)h) << 16); }
; __device__ __forceinline__ float siluf(float v) { return v * sigmf(v); }
; template <bool OUT> __device__ __forceinline__ void hgrn_item2(const PA& a, LAS unsigned char* lds, int layer, int bh, int c, int wave, int lane, const HRaw& raw) {
;     ...
; #pragma unroll
;         for (int j = 0; j < 4; ++j) {
;             float ss = (o[0][j] * o[0][j] + o[1][j] * o[1][j]) + (o[2][j] * o[2][j] + o[3][j] * o[3][j]);
;             ss += __shfl_xor(ss, 1); ss += __shfl_xor(ss, 2); ss += __shfl_xor(ss, 4); ss += __shfl_xor(ss, 8);
;             const float rs = __builtin_amdgcn_rsqf(ss * (1.f / 64.f) + EPS);
; #pragma unroll
;             for (int nt = 0; nt < 4; ++nt) { const float gt = siluf(bf1(GT[(4 * q + j) * 72 + 16 * nt + l15]));
;                 OT[(4 * q + j) * 72 + 16 * nt + l15] = (bf16)f2bf(o[nt][j] * rs * gn[nt] * gt); }
;         }
;         LDS_WAIT();
;         { const int rr = lane >> 3, cc = (lane & 7) * 8; bf16* mp = (bf16*)(a.ws + WS_MIX) + (row0 + rr) * 1024 + h * 64 + cc;
;           *(v4u*)mp = *(const LAS v4u*)(OT + rr * 72 + cc); *(v4u*)(mp + 8 * 1024) = *(const LAS v4u*)(OT + (rr + 8) * 72 + cc); }
	v_add_f32_e32 v0, v0, v1
	ds_bpermute_b32 v1, v158, v0
	s_waitcnt lgkmcnt(0)
	v_add_f32_e32 v0, v0, v1
	ds_bpermute_b32 v1, v156, v0
	s_waitcnt lgkmcnt(0)
	v_add_f32_e32 v0, v0, v1
	ds_bpermute_b32 v1, v157, v0
	s_waitcnt lgkmcnt(0)
	v_add_f32_e32 v0, v0, v1
	ds_read_u16 v1, v211 offset:4608
	ds_read_u16 v4, v211 offset:4640
	v_fmamk_f32 v0, v0, 0x3c800000, v235
	v_rsq_f32_e32 v0, v0
	s_waitcnt lgkmcnt(1)
	v_lshlrev_b32_e32 v1, 16, v1
	v_mul_f32_e32 v5, 0xbfb8aa3b, v1
	v_exp_f32_e32 v5, v5
	s_nop 0
	v_add_f32_e32 v5, 1.0, v5
	v_rcp_f32_e32 v5, v5
	s_nop 0
	v_mul_f32_e32 v1, v5, v1
	v_mul_f32_e32 v5, v10, v0
	v_mul_f32_e32 v5, v18, v5
	v_mul_f32_e32 v1, v5, v1
	v_bfe_u32 v5, v1, 16, 1
	v_add3_u32 v1, v1, v5, s73
	ds_write_b16_d16_hi v211, v1 offset:7680
	s_waitcnt lgkmcnt(1)
	v_lshlrev_b32_e32 v1, 16, v4
	v_mul_f32_e32 v4, 0xbfb8aa3b, v1
	v_exp_f32_e32 v4, v4
	s_nop 0
	v_add_f32_e32 v4, 1.0, v4
	v_rcp_f32_e32 v4, v4
	s_nop 0
	v_mul_f32_e32 v1, v4, v1
	v_mul_f32_e32 v4, v14, v0
	v_mul_f32_e32 v4, v19, v4
	v_mul_f32_e32 v1, v4, v1
	v_bfe_u32 v4, v1, 16, 1
	v_add3_u32 v1, v1, v4, s73
	ds_write_b16_d16_hi v211, v1 offset:7712
	ds_read_u16 v1, v211 offset:4672
	s_waitcnt lgkmcnt(0)
	v_lshlrev_b32_e32 v1, 16, v1
	v_mul_f32_e32 v4, 0xbfb8aa3b, v1
	v_exp_f32_e32 v4, v4
	s_nop 0
	v_add_f32_e32 v4, 1.0, v4
	v_rcp_f32_e32 v4, v4
	s_nop 0
	v_mul_f32_e32 v1, v4, v1
	v_mul_f32_e32 v4, v6, v0
	v_mul_f32_e32 v4, v17, v4
	v_mul_f32_e32 v1, v4, v1
	v_bfe_u32 v4, v1, 16, 1
	v_add3_u32 v1, v1, v4, s73
	ds_write_b16_d16_hi v211, v1 offset:7744
	ds_read_u16 v1, v211 offset:4704
	v_mul_f32_e32 v0, v2, v0
	v_mul_f32_e32 v0, v16, v0
	s_waitcnt lgkmcnt(0)
	v_lshlrev_b32_e32 v1, 16, v1
	v_mul_f32_e32 v4, 0xbfb8aa3b, v1
	v_exp_f32_e32 v4, v4
	s_nop 0
	v_add_f32_e32 v4, 1.0, v4
	v_rcp_f32_e32 v4, v4
	s_nop 0
	v_mul_f32_e32 v1, v4, v1
	v_mul_f32_e32 v0, v0, v1
	v_bfe_u32 v1, v0, 16, 1
	v_add3_u32 v0, v0, v1, s73
	ds_write_b16_d16_hi v211, v0 offset:7776
	v_mul_f32_e32 v0, v15, v15
	v_mul_f32_e32 v1, v3, v3
	v_fmac_f32_e32 v0, v11, v11
	v_fmac_f32_e32 v1, v7, v7
	v_add_f32_e32 v0, v0, v1
	ds_bpermute_b32 v1, v159, v0
	s_waitcnt lgkmcnt(0)
	v_add_f32_e32 v0, v0, v1
	ds_bpermute_b32 v1, v158, v0
	s_waitcnt lgkmcnt(0)
	v_add_f32_e32 v0, v0, v1
	ds_bpermute_b32 v1, v156, v0
	s_waitcnt lgkmcnt(0)
	v_add_f32_e32 v0, v0, v1
	ds_bpermute_b32 v1, v157, v0
	s_waitcnt lgkmcnt(0)
	v_add_f32_e32 v0, v0, v1
	ds_read_u16 v1, v212 offset:4608
	ds_read_u16 v2, v212 offset:4640
	v_fmamk_f32 v0, v0, 0x3c800000, v235
	v_rsq_f32_e32 v0, v0
	s_waitcnt lgkmcnt(1)
	v_lshlrev_b32_e32 v1, 16, v1
	v_mul_f32_e32 v4, 0xbfb8aa3b, v1
	v_exp_f32_e32 v4, v4
	s_nop 0
	v_add_f32_e32 v4, 1.0, v4
	v_rcp_f32_e32 v4, v4
	s_nop 0
	v_mul_f32_e32 v1, v4, v1
	v_mul_f32_e32 v4, v11, v0
	v_mul_f32_e32 v4, v18, v4
	v_mul_f32_e32 v1, v4, v1
	v_bfe_u32 v4, v1, 16, 1
	v_add3_u32 v1, v1, v4, s73
	ds_write_b16_d16_hi v212, v1 offset:7680
	s_waitcnt lgkmcnt(1)
	v_lshlrev_b32_e32 v1, 16, v2
	v_mul_f32_e32 v2, 0xbfb8aa3b, v1
	v_exp_f32_e32 v2, v2
	s_nop 0
	v_add_f32_e32 v2, 1.0, v2
	v_rcp_f32_e32 v2, v2
	s_nop 0
	v_mul_f32_e32 v1, v2, v1
	v_mul_f32_e32 v2, v15, v0
	v_mul_f32_e32 v2, v19, v2
	v_mul_f32_e32 v1, v2, v1
	v_bfe_u32 v2, v1, 16, 1
	v_add3_u32 v1, v1, v2, s73
	ds_write_b16_d16_hi v212, v1 offset:7712
	ds_read_u16 v1, v212 offset:4672
	s_waitcnt lgkmcnt(0)
	v_lshlrev_b32_e32 v1, 16, v1
	v_mul_f32_e32 v2, 0xbfb8aa3b, v1
	v_exp_f32_e32 v2, v2
	s_nop 0
	v_add_f32_e32 v2, 1.0, v2
	v_rcp_f32_e32 v2, v2
	s_nop 0
	v_mul_f32_e32 v1, v2, v1
	v_mul_f32_e32 v2, v7, v0
	v_mul_f32_e32 v2, v17, v2
	v_mul_f32_e32 v1, v2, v1
	v_bfe_u32 v2, v1, 16, 1
	v_add3_u32 v1, v1, v2, s73
	ds_write_b16_d16_hi v212, v1 offset:7744
	ds_read_u16 v1, v212 offset:4704
	v_mul_f32_e32 v0, v3, v0
	v_mul_f32_e32 v0, v16, v0
	s_waitcnt lgkmcnt(0)
	v_lshlrev_b32_e32 v1, 16, v1
	v_mul_f32_e32 v2, 0xbfb8aa3b, v1
	v_exp_f32_e32 v2, v2
	s_nop 0
	v_add_f32_e32 v2, 1.0, v2
	v_rcp_f32_e32 v2, v2
	s_nop 0
	v_mul_f32_e32 v1, v2, v1
	v_mul_f32_e32 v0, v0, v1
	v_bfe_u32 v1, v0, 16, 1
	v_add3_u32 v0, v0, v1, s73
	ds_write_b16_d16_hi v212, v0 offset:7776
	v_lshlrev_b64 v[0:1], 11, v[196:197]
	v_lshl_add_u64 v[0:1], s[90:91], 0, v[0:1]
	s_waitcnt lgkmcnt(0)
	v_lshl_add_u64 v[0:1], v[0:1], 0, s[62:63]
	v_lshl_add_u64 v[4:5], v[0:1], 0, v[220:221]
	ds_read_b128 v[0:3], v204 offset:7680
	s_waitcnt lgkmcnt(0)
	global_store_dwordx4 v[4:5], v[0:3], off
	ds_read_b128 v[0:3], v204 offset:8832
	v_add_co_u32_e32 v4, vcc, 0x4000, v4
	s_nop 1
	v_addc_co_u32_e32 v5, vcc, 0, v5, vcc
	s_waitcnt lgkmcnt(0)
	global_store_dwordx4 v[4:5], v[0:3], off
	s_cbranch_scc1 .LBB0_756
; #define LAS __attribute__((address_space(3)))
; #define LDS_WAIT() asm volatile("s_waitcnt lgkmcnt(0)" ::: "memory")
; __device__ __forceinline__ float sigmf(float v) { return __builtin_amdgcn_rcpf(1.0f + __builtin_amdgcn_exp2f(-1.4426950408889634f * v)); }
; template <bool OUT> __device__ __forceinline__ HRaw hgrn_load(const PA& a, int bh, int c, int wave, int lane) {
;     const bf16* pr = (const bf16*)(a.ws + WS_PROJ) + ((size_t)(bh >> 2) * T + (size_t)c * 128 + wave * 16 + (lane >> 3)) * DIN + (bh & 3) * 64 + (lane & 7) * 8;
;     HRaw r;
; #pragma unroll
;     for (int k = 0; k < 2; ++k) { r.f[k] = *(const v4u*)(pr + (size_t)(8 * k) * DIN + 256); r.v[k] = *(const v4u*)(pr + (size_t)(8 * k) * DIN + 512);
;         if (OUT) { r.q[k] = *(const v4u*)(pr + (size_t)(8 * k) * DIN); r.g[k] = *(const v4u*)(pr + (size_t)(8 * k) * DIN + 768); } }
;     return r;
; }
; template <bool OUT> __device__ __forceinline__ void hgrn_item2(const PA& a, LAS unsigned char* lds, int layer, int bh, int c, int wave, int lane, const HRaw& raw) {
;     const int b = bh >> 2, h = bh & 3, item = bh * 64 + c;
;     float* HU = (float*)(a.ws + WS_HU); float* HA = (float*)(a.ws + WS_HA);
;     LAS unsigned char* wb = lds + wave * 12288;
;     LAS bf16* QT = (LAS bf16*)wb; LAS bf16* KT = (LAS bf16*)(wb + 2304); LAS bf16* KHT = (LAS bf16*)(wb + 4608); LAS bf16* VT = (LAS bf16*)(wb + 7680); LAS bf16* P = (LAS bf16*)(wb + 10752);
;     LAS float* DL = (LAS float*)(wb + 11520); LAS float* E7L = (LAS float*)(wb + 11776);
;     LAS bf16* RF = (LAS bf16*)wb; LAS bf16* RV = (LAS bf16*)(wb + 2304); LAS bf16* RQ = (LAS bf16*)(wb + 4608);
;     LAS bf16* GT = KHT; LAS bf16* OT = VT;
;     LAS float* SBUF = (LAS float*)(lds + 98304); LAS float* DALL = (LAS float*)(lds + 114688);
;     const int l15 = lane & 15, q = lane >> 4;
;     const size_t row0 = (size_t)b * T + (size_t)c * 128 + wave * 16;
;     const bf16x8 zero8 = {0, 0, 0, 0, 0, 0, 0, 0};
;     __syncthreads();
;     {
;         const int rr = lane >> 3, cc = (lane & 7) * 8;
; #pragma unroll
;         for (int k = 0; k < 2; ++k) { *(LAS v4u*)(RF + (rr + 8 * k) * 72 + cc) = raw.f[k]; *(LAS v4u*)(RV + (rr + 8 * k) * 72 + cc) = raw.v[k]; if (OUT) *(LAS v4u*)(RQ + (rr + 8 * k) * 72 + cc) = raw.q[k]; }
;         LDS_WAIT();
;         const float lb = (layer == 0) ? 0.f : sigmf(a.in[4][256 + h * 64 + lane] - a.in[4][h * 64 + lane]);
.LBB0_708:
	s_ashr_i32 s0, s8, 7
	s_and_b32 s12, s8, 31
	s_ashr_i32 s1, s0, 31
	s_lshl_b64 s[0:1], s[0:1], 13
	s_lshl_b32 s9, s12, 7
	s_or_b32 s14, s0, s9
	s_mov_b32 s15, s1
	v_lshl_add_u64 v[198:199], s[14:15], 0, v[188:189]
	v_mov_b64_e32 v[0:1], s[60:61]
	v_mad_u64_u32 v[2:3], s[14:15], v198, s93, v[0:1]
	s_ashr_i32 s11, s8, 5
	v_mov_b32_e32 v4, v3
	v_mad_u64_u32 v[4:5], s[14:15], v199, s93, v[4:5]
	s_lshl_b32 s9, s11, 7
	v_mov_b32_e32 v3, v4
	s_and_b32 s62, s9, 0x180
	s_xor_b32 s9, s12, 63
	v_lshl_add_u64 v[2:3], v[2:3], 0, s[62:63]
	s_lshl_b32 s10, s9, 7
	v_lshl_add_u64 v[2:3], v[2:3], 0, v[220:221]
	s_mov_b32 s13, 0xe000
	s_or_b32 s0, s0, s10
	global_load_dwordx4 v[40:43], v[2:3], off offset:512
	global_load_dwordx4 v[44:47], v[2:3], off offset:1024
	global_load_dwordx4 v[48:51], v[2:3], off
	global_load_dwordx4 v[32:35], v[2:3], off offset:1536
	v_add_co_u32_e32 v2, vcc, s13, v2
	v_lshl_add_u64 v[196:197], s[0:1], 0, v[188:189]
	s_nop 0
	v_addc_co_u32_e32 v3, vcc, 0, v3, vcc
	v_mad_u64_u32 v[0:1], s[0:1], v196, s93, v[0:1]
	global_load_dwordx4 v[52:55], v[2:3], off offset:512
	global_load_dwordx4 v[56:59], v[2:3], off offset:1024
	global_load_dwordx4 v[60:63], v[2:3], off
	global_load_dwordx4 v[36:39], v[2:3], off offset:1536
	v_mov_b32_e32 v2, v1
	v_mad_u64_u32 v[2:3], s[0:1], v197, s93, v[2:3]
	v_mov_b32_e32 v1, v2
	v_lshl_add_u64 v[0:1], v[0:1], 0, s[62:63]
	v_lshl_add_u64 v[4:5], v[0:1], 0, v[220:221]
	global_load_dwordx4 v[8:11], v[4:5], off offset:512
	global_load_dwordx4 v[12:15], v[4:5], off offset:1024
	global_load_dwordx4 v[16:19], v[4:5], off
	global_load_dwordx4 v[0:3], v[4:5], off offset:1536
	v_add_co_u32_e32 v4, vcc, s13, v4
	s_and_b32 s10, s11, 3
	s_nop 0
	v_addc_co_u32_e32 v5, vcc, 0, v5, vcc
	global_load_dwordx4 v[20:23], v[4:5], off offset:512
	global_load_dwordx4 v[24:27], v[4:5], off offset:1024
	global_load_dwordx4 v[28:31], v[4:5], off
	s_nop 0
	global_load_dwordx4 v[4:7], v[4:5], off offset:1536
	s_waitcnt vmcnt(63) expcnt(7) lgkmcnt(15)
	s_barrier
	s_andn2_b64 vcc, exec, s[4:5]
	s_waitcnt vmcnt(15)
	ds_write_b128 v201, v[40:43]
	s_waitcnt vmcnt(14)
	ds_write_b128 v201, v[44:47] offset:2304
	s_waitcnt vmcnt(13)
	ds_write_b128 v201, v[48:51] offset:4608
	s_waitcnt vmcnt(11)
	ds_write_b128 v201, v[52:55] offset:1152
	s_waitcnt vmcnt(10)
	ds_write_b128 v201, v[56:59] offset:3456
	s_waitcnt vmcnt(9)
	ds_write_b128 v201, v[60:63] offset:5760
	s_waitcnt lgkmcnt(0)
	v_cndmask_b32_e64 v41, 0, 1, s[4:5]
	v_mov_b32_e32 v40, 0
	v_cmp_ne_u32_e64 s[48:49], 1, v41
	v_mov_b32_e32 v51, 0
	s_cbranch_vccnz .LBB0_710
	v_lshlrev_b32_e32 v41, 5, v234
	v_add_u32_e32 v41, 0x1e000, v41
	ds_read_b32 v51, v41 offset:16
	s_waitcnt lgkmcnt(0)

; #define LAS __attribute__((address_space(3)))
; __device__ __forceinline__ unsigned pk2(float lo, float hi) { return f2bf(lo) | (f2bf(hi) << 16); }
; template <bool OUT> __device__ __forceinline__ void hgrn_item2(const PA& a, LAS unsigned char* lds, int layer, int bh, int c, int wave, int lane, const HRaw& raw) {
;     ...
;         for (int mt = 0; mt < 4; ++mt) { const f32x4 Ev = *(const LAS f32x4*)(E7L + 16 * mt + 4 * q);
; #pragma unroll
;             for (int nt = 0; nt < 4; ++nt) Sp[mt][nt] = Sp[mt][nt] * Ev; }
; #pragma unroll
;         for (int nt = 0; nt < 4; ++nt)
; #pragma unroll
;             for (int ks = 0; ks < 2; ++ks) {
;                 const f32x4 s0 = Sp[2 * ks][nt], s1 = Sp[2 * ks + 1][nt];
;                 const bf16x8 bfrag = __builtin_bit_cast(bf16x8, (v4u){pk2(s0[0], s0[1]), pk2(s0[2], s0[3]), pk2(s1[0], s1[1]), pk2(s1[2], s1[3])});
;                 o[nt] = __builtin_amdgcn_mfma_f32_16x16x32_bf16(qf[ks], bfrag, o[nt], 0, 0, 0);
;             }
.LBB0_732:
	v_add_u32_e32 v251, s3, v208
	ds_read_b128 v[64:67], v251 offset:11776
	ds_read_b128 v[80:83], v251 offset:11904
	v_mfma_f32_16x16x32_bf16 v[44:47], v[104:107], v[44:47], 0
	v_readlane_b32 s0, v253, 29
	v_readlane_b32 s1, v253, 30
	s_waitcnt lgkmcnt(1)
	v_pk_mul_f32 v[84:85], v[138:139], v[66:67]
	v_pk_mul_f32 v[72:73], v[154:155], v[66:67]
	v_pk_mul_f32 v[60:61], v[170:171], v[66:67]
	v_pk_mul_f32 v[56:57], v[182:183], v[66:67]
	ds_read_b128 v[66:69], v251 offset:11840
	v_mfma_f32_16x16x32_bf16 v[52:55], v[104:107], v[52:55], 0
	v_mul_f32_e64 v86, v136, v64
	v_mul_f32_e64 v87, v137, v65
	v_pk_mul_f32 v[74:75], v[152:153], v[64:65]
	v_pk_mul_f32 v[62:63], v[168:169], v[64:65]
	v_pk_mul_f32 v[58:59], v[180:181], v[64:65]
	s_waitcnt lgkmcnt(0)
	v_pk_mul_f32 v[88:89], v[134:135], v[68:69]
	v_pk_mul_f32 v[92:93], v[126:127], v[68:69]
	v_pk_mul_f32 v[76:77], v[146:147], v[68:69]
	v_pk_mul_f32 v[64:65], v[162:163], v[68:69]
	v_pk_mul_f32 v[96:97], v[158:159], v[82:83]
	v_pk_mul_f32 v[98:99], v[156:157], v[80:81]
	v_pk_mul_f32 v[100:101], v[174:175], v[82:83]
	v_pk_mul_f32 v[102:103], v[172:173], v[80:81]
	v_pk_mul_f32 v[104:105], v[178:179], v[82:83]
	v_pk_mul_f32 v[106:107], v[176:177], v[80:81]
	v_pk_mul_f32 v[68:69], v[186:187], v[82:83]
	v_pk_mul_f32 v[70:71], v[184:185], v[80:81]
	ds_read_b128 v[80:83], v251 offset:11968
	v_pk_mul_f32 v[90:91], v[132:133], v[66:67]
	v_pk_mul_f32 v[94:95], v[124:125], v[66:67]
	v_pk_mul_f32 v[78:79], v[144:145], v[66:67]
	v_pk_mul_f32 v[66:67], v[160:161], v[66:67]
	s_waitcnt lgkmcnt(0)
	v_pk_mul_f32 v[110:111], v[140:141], v[80:81]
	v_pk_mul_f32 v[114:115], v[128:129], v[80:81]
	v_pk_mul_f32 v[118:119], v[148:149], v[80:81]
	v_pk_mul_f32 v[122:123], v[164:165], v[80:81]
	v_bfe_u32 v80, v86, 16, 1
	v_add3_u32 v80, v86, v80, s73
	v_bfe_u32 v81, v87, 16, 1
	v_lshrrev_b32_e32 v80, 16, v80
	v_add3_u32 v81, v87, v81, s73
	v_and_or_b32 v80, v81, s26, v80
	v_bfe_u32 v81, v84, 16, 1
	v_pk_mul_f32 v[108:109], v[142:143], v[82:83]
	v_pk_mul_f32 v[112:113], v[130:131], v[82:83]
	v_pk_mul_f32 v[116:117], v[150:151], v[82:83]
	v_pk_mul_f32 v[120:121], v[166:167], v[82:83]
	v_add3_u32 v81, v84, v81, s73
	v_bfe_u32 v82, v85, 16, 1
	v_lshrrev_b32_e32 v81, 16, v81
	v_add3_u32 v82, v85, v82, s73
	v_and_or_b32 v81, v82, s26, v81
	v_bfe_u32 v82, v90, 16, 1
	v_add3_u32 v82, v90, v82, s73
	v_bfe_u32 v83, v91, 16, 1
	v_lshrrev_b32_e32 v82, 16, v82
	v_add3_u32 v83, v91, v83, s73
	v_and_or_b32 v82, v83, s26, v82
	v_bfe_u32 v83, v88, 16, 1
	v_add3_u32 v83, v88, v83, s73
	v_bfe_u32 v84, v89, 16, 1
	v_lshrrev_b32_e32 v83, 16, v83
	v_add3_u32 v84, v89, v84, s73
	v_and_or_b32 v83, v84, s26, v83
	v_bfe_u32 v84, v109, 16, 1
	v_add3_u32 v84, v109, v84, s73
	v_mfma_f32_16x16x32_bf16 v[40:43], v[48:51], v[80:83], v[40:43]
	v_bfe_u32 v80, v98, 16, 1
	v_add3_u32 v80, v98, v80, s73
	v_bfe_u32 v81, v99, 16, 1
	v_lshrrev_b32_e32 v80, 16, v80
	v_add3_u32 v81, v99, v81, s73
	v_and_or_b32 v80, v81, s26, v80
	v_bfe_u32 v81, v96, 16, 1
	v_add3_u32 v81, v96, v81, s73
	v_bfe_u32 v82, v97, 16, 1
	v_lshrrev_b32_e32 v81, 16, v81
	v_add3_u32 v82, v97, v82, s73
	v_and_or_b32 v81, v82, s26, v81
	v_bfe_u32 v82, v110, 16, 1
	v_add3_u32 v82, v110, v82, s73
	v_bfe_u32 v83, v111, 16, 1
	v_lshrrev_b32_e32 v82, 16, v82
	v_add3_u32 v83, v111, v83, s73
	v_and_or_b32 v82, v83, s26, v82
	v_bfe_u32 v83, v108, 16, 1
	v_add3_u32 v83, v108, v83, s73
	v_lshrrev_b32_e32 v83, 16, v83
	v_and_or_b32 v83, v84, s26, v83
	s_lshl_b32 s62, s10, 7
	s_lshl_b32 s12, s10, 6
	v_mfma_f32_16x16x32_bf16 v[40:43], v[32:35], v[80:83], v[40:43]
	v_bfe_u32 v80, v74, 16, 1
	v_add3_u32 v74, v74, v80, s73
	v_bfe_u32 v80, v75, 16, 1
	v_lshrrev_b32_e32 v74, 16, v74
	v_add3_u32 v75, v75, v80, s73
	v_and_or_b32 v80, v75, s26, v74
	v_bfe_u32 v74, v72, 16, 1
	v_add3_u32 v72, v72, v74, s73
	v_bfe_u32 v74, v73, 16, 1
	v_lshrrev_b32_e32 v72, 16, v72
	v_add3_u32 v73, v73, v74, s73
	v_and_or_b32 v81, v73, s26, v72
	v_bfe_u32 v72, v94, 16, 1
	v_add3_u32 v72, v94, v72, s73
	v_bfe_u32 v73, v95, 16, 1
	v_lshrrev_b32_e32 v72, 16, v72
	v_add3_u32 v73, v95, v73, s73
	v_and_or_b32 v82, v73, s26, v72
	v_bfe_u32 v72, v92, 16, 1
	v_add3_u32 v72, v92, v72, s73
	v_bfe_u32 v73, v93, 16, 1
	v_lshrrev_b32_e32 v72, 16, v72
	v_add3_u32 v73, v93, v73, s73
	v_and_or_b32 v83, v73, s26, v72
	v_bfe_u32 v72, v102, 16, 1
	v_add3_u32 v72, v102, v72, s73
	v_bfe_u32 v73, v103, 16, 1
	v_lshrrev_b32_e32 v72, 16, v72
	v_add3_u32 v73, v103, v73, s73
	v_and_or_b32 v72, v73, s26, v72
	v_bfe_u32 v73, v100, 16, 1
	v_add3_u32 v73, v100, v73, s73
	v_bfe_u32 v74, v101, 16, 1
	v_lshrrev_b32_e32 v73, 16, v73
	v_add3_u32 v74, v101, v74, s73
	v_and_or_b32 v73, v74, s26, v73
	v_bfe_u32 v74, v114, 16, 1
	v_add3_u32 v74, v114, v74, s73
	v_bfe_u32 v75, v115, 16, 1
	v_lshrrev_b32_e32 v74, 16, v74
	v_add3_u32 v75, v115, v75, s73
	v_mfma_f32_16x16x32_bf16 v[44:47], v[48:51], v[80:83], v[44:47]
	v_and_or_b32 v74, v75, s26, v74
	v_bfe_u32 v75, v112, 16, 1
	v_add3_u32 v75, v112, v75, s73
	v_bfe_u32 v80, v113, 16, 1
	v_lshrrev_b32_e32 v75, 16, v75
	v_add3_u32 v80, v113, v80, s73
	v_and_or_b32 v75, v80, s26, v75
	s_nop 1
	v_mfma_f32_16x16x32_bf16 v[44:47], v[32:35], v[72:75], v[44:47]
	v_bfe_u32 v72, v62, 16, 1
	v_add3_u32 v62, v62, v72, s73
	v_bfe_u32 v72, v63, 16, 1
	v_lshrrev_b32_e32 v62, 16, v62
	v_add3_u32 v63, v63, v72, s73
	v_and_or_b32 v72, v63, s26, v62
	v_bfe_u32 v62, v60, 16, 1
	v_add3_u32 v60, v60, v62, s73
	v_bfe_u32 v62, v61, 16, 1
	v_lshrrev_b32_e32 v60, 16, v60
	v_add3_u32 v61, v61, v62, s73
	v_and_or_b32 v73, v61, s26, v60
	v_bfe_u32 v60, v78, 16, 1
	v_add3_u32 v60, v78, v60, s73
	v_bfe_u32 v61, v79, 16, 1
	v_lshrrev_b32_e32 v60, 16, v60
; __device__ __forceinline__ unsigned f2bf(float f) { unsigned u = __builtin_bit_cast(unsigned, f); return (u + 0x7fffu + ((u >> 16) & 1u)) >> 16; }
; __device__ __forceinline__ float bf1(bf16 h) { return __uint_as_float(((unsigned)h) << 16); }
; __device__ __forceinline__ float siluf(float v) { return v * sigmf(v); }
; template <bool OUT> __device__ __forceinline__ void hgrn_item2(const PA& a, LAS unsigned char* lds, int layer, int bh, int c, int wave, int lane, const HRaw& raw) {
;     ...
;         float gn[4];
; #pragma unroll
;         for (int nt = 0; nt < 4; ++nt) gn[nt] = a.in[5][layer * 64 + 16 * nt + l15];
; #pragma unroll
;         for (int j = 0; j < 4; ++j) {
;             float ss = (o[0][j] * o[0][j] + o[1][j] * o[1][j]) + (o[2][j] * o[2][j] + o[3][j] * o[3][j]);
;             ss += __shfl_xor(ss, 1); ss += __shfl_xor(ss, 2); ss += __shfl_xor(ss, 4); ss += __shfl_xor(ss, 8);
;             const float rs = __builtin_amdgcn_rsqf(ss * (1.f / 64.f) + EPS);
; #pragma unroll
;             for (int nt = 0; nt < 4; ++nt) { const float gt = siluf(bf1(GT[(4 * q + j) * 72 + 16 * nt + l15]));
;                 OT[(4 * q + j) * 72 + 16 * nt + l15] = (bf16)f2bf(o[nt][j] * rs * gn[nt] * gt); }
	v_add3_u32 v61, v79, v61, s73
	v_and_or_b32 v74, v61, s26, v60
	v_bfe_u32 v60, v76, 16, 1
	v_add3_u32 v60, v76, v60, s73
	v_bfe_u32 v61, v77, 16, 1
	v_lshrrev_b32_e32 v60, 16, v60
	v_add3_u32 v61, v77, v61, s73
	v_and_or_b32 v75, v61, s26, v60
	v_bfe_u32 v60, v106, 16, 1
	v_add3_u32 v60, v106, v60, s73
	v_bfe_u32 v61, v107, 16, 1
	v_lshrrev_b32_e32 v60, 16, v60
	v_add3_u32 v61, v107, v61, s73
	v_and_or_b32 v60, v61, s26, v60
	v_bfe_u32 v61, v104, 16, 1
	v_add3_u32 v61, v104, v61, s73
	v_bfe_u32 v62, v105, 16, 1
	v_lshrrev_b32_e32 v61, 16, v61
	v_add3_u32 v62, v105, v62, s73
	v_and_or_b32 v61, v62, s26, v61
	v_bfe_u32 v62, v118, 16, 1
	v_add3_u32 v62, v118, v62, s73
	v_bfe_u32 v63, v119, 16, 1
	v_lshrrev_b32_e32 v62, 16, v62
	v_add3_u32 v63, v119, v63, s73
	v_mfma_f32_16x16x32_bf16 v[36:39], v[48:51], v[72:75], v[36:39]
	v_and_or_b32 v62, v63, s26, v62
	v_bfe_u32 v63, v116, 16, 1
	v_add3_u32 v63, v116, v63, s73
	v_bfe_u32 v72, v117, 16, 1
	v_lshrrev_b32_e32 v63, 16, v63
	v_add3_u32 v72, v117, v72, s73
	v_and_or_b32 v63, v72, s26, v63
	s_nop 1
	v_mfma_f32_16x16x32_bf16 v[36:39], v[32:35], v[60:63], v[36:39]
	v_bfe_u32 v60, v58, 16, 1
	v_add3_u32 v58, v58, v60, s73
	v_bfe_u32 v60, v59, 16, 1
	v_lshrrev_b32_e32 v58, 16, v58
	v_add3_u32 v59, v59, v60, s73
	v_and_or_b32 v58, v59, s26, v58
	v_bfe_u32 v59, v56, 16, 1
	v_add3_u32 v56, v56, v59, s73
	v_bfe_u32 v59, v57, 16, 1
	v_lshrrev_b32_e32 v56, 16, v56
	v_add3_u32 v57, v57, v59, s73
	v_and_or_b32 v59, v57, s26, v56
	v_bfe_u32 v56, v66, 16, 1
	v_add3_u32 v56, v66, v56, s73
	v_bfe_u32 v57, v67, 16, 1
	v_lshrrev_b32_e32 v56, 16, v56
	v_add3_u32 v57, v67, v57, s73
	v_and_or_b32 v60, v57, s26, v56
	v_bfe_u32 v56, v64, 16, 1
	v_add3_u32 v56, v64, v56, s73
	v_bfe_u32 v57, v65, 16, 1
	v_lshrrev_b32_e32 v56, 16, v56
	v_add3_u32 v57, v65, v57, s73
	v_and_or_b32 v61, v57, s26, v56
	v_bfe_u32 v56, v121, 16, 1
	v_add3_u32 v56, v121, v56, s73
	v_mfma_f32_16x16x32_bf16 v[48:51], v[48:51], v[58:61], v[52:55]
	s_nop 2
	v_bfe_u32 v52, v70, 16, 1
	v_add3_u32 v52, v70, v52, s73
	v_bfe_u32 v53, v71, 16, 1
	v_lshrrev_b32_e32 v52, 16, v52
	v_add3_u32 v53, v71, v53, s73
	v_and_or_b32 v52, v53, s26, v52
	v_bfe_u32 v53, v68, 16, 1
	v_add3_u32 v53, v68, v53, s73
	v_bfe_u32 v54, v69, 16, 1
	v_lshrrev_b32_e32 v53, 16, v53
	v_add3_u32 v54, v69, v54, s73
	v_and_or_b32 v53, v54, s26, v53
	v_bfe_u32 v54, v122, 16, 1
	v_add3_u32 v54, v122, v54, s73
	v_bfe_u32 v55, v123, 16, 1
	v_lshrrev_b32_e32 v54, 16, v54
	v_add3_u32 v55, v123, v55, s73
	v_and_or_b32 v54, v55, s26, v54
	v_bfe_u32 v55, v120, 16, 1
	v_add3_u32 v55, v120, v55, s73
	v_lshrrev_b32_e32 v55, 16, v55
	v_and_or_b32 v55, v56, s26, v55
	s_nop 1
	v_mfma_f32_16x16x32_bf16 v[32:35], v[32:35], v[52:55], v[48:51]
	s_nop 2
	v_lshlrev_b32_e32 v48, 5, v234
	v_add_u32_e32 v48, 0x1e000, v48
	ds_read_b128 v[48:51], v48
	s_nop 3
	v_and_b32_e32 v53, 64, v237
	v_xor_b32_e32 v52, 1, v237
	v_add_u32_e32 v53, 64, v53
	v_cmp_lt_i32_e32 vcc, v52, v53
	s_nop 1
	v_cndmask_b32_e32 v52, v237, v52, vcc
	v_lshlrev_b32_e32 v159, 2, v52
	v_xor_b32_e32 v52, 2, v237
	v_cmp_lt_i32_e32 vcc, v52, v53
	s_nop 1
	v_cndmask_b32_e32 v52, v237, v52, vcc
	v_lshlrev_b32_e32 v158, 2, v52
	v_xor_b32_e32 v52, 4, v237
	v_cmp_lt_i32_e32 vcc, v52, v53
	s_nop 1
	v_cndmask_b32_e32 v52, v237, v52, vcc
	v_lshlrev_b32_e32 v156, 2, v52
	v_xor_b32_e32 v52, 8, v237
	v_cmp_lt_i32_e32 vcc, v52, v53
	v_mul_f32_e32 v53, v32, v32
	v_fmac_f32_e32 v53, v36, v36
	v_cndmask_b32_e32 v52, v237, v52, vcc
	v_lshlrev_b32_e32 v157, 2, v52
	v_mul_f32_e32 v52, v44, v44
	v_fmac_f32_e32 v52, v40, v40
	v_add_f32_e32 v52, v52, v53
	ds_bpermute_b32 v53, v159, v52
	s_waitcnt lgkmcnt(0)
	v_add_f32_e32 v52, v52, v53
	ds_bpermute_b32 v53, v158, v52
	s_waitcnt lgkmcnt(0)
	v_add_f32_e32 v52, v52, v53
	ds_bpermute_b32 v53, v156, v52
	s_waitcnt lgkmcnt(0)
	v_add_f32_e32 v52, v52, v53
	ds_bpermute_b32 v53, v157, v52
	s_waitcnt lgkmcnt(0)
	v_add_f32_e32 v52, v52, v53
	ds_read_u16 v53, v209 offset:4608
	ds_read_u16 v54, v209 offset:4640
	v_fmamk_f32 v52, v52, 0x3c800000, v235
	v_rsq_f32_e32 v52, v52
	s_waitcnt lgkmcnt(0)
	v_lshlrev_b32_e32 v53, 16, v53
	v_mul_f32_e32 v55, 0xbfb8aa3b, v53
	v_exp_f32_e32 v55, v55
	v_mul_f32_e32 v40, v40, v52
	v_mul_f32_e32 v44, v44, v52
	v_mul_f32_e32 v36, v36, v52
	v_add_f32_e32 v55, 1.0, v55
	v_rcp_f32_e32 v55, v55
	v_mul_f32_e32 v32, v32, v52
	v_mul_f32_e32 v53, v55, v53
	s_waitcnt vmcnt(0) lgkmcnt(0)
	v_mul_f32_e32 v40, v50, v40
	v_mul_f32_e32 v40, v40, v53
	v_bfe_u32 v53, v40, 16, 1
	v_add3_u32 v40, v40, v53, s73
	ds_write_b16_d16_hi v209, v40 offset:7680
	v_lshlrev_b32_e32 v40, 16, v54
	v_mul_f32_e32 v53, 0xbfb8aa3b, v40
	v_exp_f32_e32 v53, v53
	v_mul_f32_e32 v44, v51, v44
	v_mul_f32_e32 v36, v49, v36
	v_mul_f32_e32 v32, v48, v32
	v_add_f32_e32 v53, 1.0, v53
	v_rcp_f32_e32 v53, v53
	s_nop 0
	v_mul_f32_e32 v40, v53, v40
	v_mul_f32_e32 v40, v44, v40
	v_bfe_u32 v44, v40, 16, 1
	v_add3_u32 v40, v40, v44, s73
	ds_write_b16_d16_hi v209, v40 offset:7712
	ds_read_u16 v40, v209 offset:4672
	s_waitcnt lgkmcnt(0)
	v_lshlrev_b32_e32 v40, 16, v40
	v_mul_f32_e32 v44, 0xbfb8aa3b, v40
	v_exp_f32_e32 v44, v44
	s_nop 0
	v_add_f32_e32 v44, 1.0, v44
	v_rcp_f32_e32 v44, v44
	s_nop 0
	v_mul_f32_e32 v40, v44, v40
	v_mul_f32_e32 v36, v36, v40
	v_bfe_u32 v40, v36, 16, 1
	v_add3_u32 v36, v36, v40, s73
	ds_write_b16_d16_hi v209, v36 offset:7744
	ds_read_u16 v36, v209 offset:4704
	s_waitcnt lgkmcnt(0)
; __device__ __forceinline__ unsigned f2bf(float f) { unsigned u = __builtin_bit_cast(unsigned, f); return (u + 0x7fffu + ((u >> 16) & 1u)) >> 16; }
; __device__ __forceinline__ float bf1(bf16 h) { return __uint_as_float(((unsigned)h) << 16); }
; __device__ __forceinline__ float siluf(float v) { return v * sigmf(v); }
; template <bool OUT> __device__ __forceinline__ void hgrn_item2(const PA& a, LAS unsigned char* lds, int layer, int bh, int c, int wave, int lane, const HRaw& raw) {
;     ...
; #pragma unroll
;         for (int j = 0; j < 4; ++j) {
;             float ss = (o[0][j] * o[0][j] + o[1][j] * o[1][j]) + (o[2][j] * o[2][j] + o[3][j] * o[3][j]);
;             ss += __shfl_xor(ss, 1); ss += __shfl_xor(ss, 2); ss += __shfl_xor(ss, 4); ss += __shfl_xor(ss, 8);
;             const float rs = __builtin_amdgcn_rsqf(ss * (1.f / 64.f) + EPS);
; #pragma unroll
;             for (int nt = 0; nt < 4; ++nt) { const float gt = siluf(bf1(GT[(4 * q + j) * 72 + 16 * nt + l15]));
;                 OT[(4 * q + j) * 72 + 16 * nt + l15] = (bf16)f2bf(o[nt][j] * rs * gn[nt] * gt); }
;         }
	v_lshlrev_b32_e32 v36, 16, v36
	v_mul_f32_e32 v40, 0xbfb8aa3b, v36
	v_exp_f32_e32 v40, v40
	s_nop 0
	v_add_f32_e32 v40, 1.0, v40
	v_rcp_f32_e32 v40, v40
	s_nop 0
	v_mul_f32_e32 v36, v40, v36
	v_mul_f32_e32 v32, v32, v36
	v_bfe_u32 v36, v32, 16, 1
	v_add3_u32 v32, v32, v36, s73
	ds_write_b16_d16_hi v209, v32 offset:7776
	v_mul_f32_e32 v32, v45, v45
	v_mul_f32_e32 v36, v33, v33
	v_fmac_f32_e32 v32, v41, v41
	v_fmac_f32_e32 v36, v37, v37
	v_add_f32_e32 v32, v32, v36
	ds_bpermute_b32 v36, v159, v32
	s_waitcnt lgkmcnt(0)
	v_add_f32_e32 v32, v32, v36
	ds_bpermute_b32 v36, v158, v32
	s_waitcnt lgkmcnt(0)
	v_add_f32_e32 v32, v32, v36
	ds_bpermute_b32 v36, v156, v32
	s_waitcnt lgkmcnt(0)
	v_add_f32_e32 v32, v32, v36
	ds_bpermute_b32 v36, v157, v32
	s_waitcnt lgkmcnt(0)
	v_add_f32_e32 v32, v32, v36
	ds_read_u16 v36, v210 offset:4608
	ds_read_u16 v40, v210 offset:4640
	v_fmamk_f32 v32, v32, 0x3c800000, v235
	v_rsq_f32_e32 v32, v32
	s_waitcnt lgkmcnt(1)
	v_lshlrev_b32_e32 v36, 16, v36
	v_mul_f32_e32 v44, 0xbfb8aa3b, v36
	v_exp_f32_e32 v44, v44
	v_mul_f32_e32 v41, v41, v32
	v_mul_f32_e32 v41, v50, v41
	v_mul_f32_e32 v37, v37, v32
	v_add_f32_e32 v44, 1.0, v44
	v_rcp_f32_e32 v44, v44
	v_mul_f32_e32 v37, v49, v37
	v_mul_f32_e32 v36, v44, v36
	v_mul_f32_e32 v36, v41, v36
	v_bfe_u32 v41, v36, 16, 1
	v_add3_u32 v36, v36, v41, s73
	ds_write_b16_d16_hi v210, v36 offset:7680
	s_waitcnt lgkmcnt(1)
	v_lshlrev_b32_e32 v36, 16, v40
	v_mul_f32_e32 v40, 0xbfb8aa3b, v36
	v_exp_f32_e32 v40, v40
	s_nop 0
	v_add_f32_e32 v40, 1.0, v40
	v_rcp_f32_e32 v40, v40
	s_nop 0
	v_mul_f32_e32 v36, v40, v36
	v_mul_f32_e32 v40, v45, v32
	v_mul_f32_e32 v40, v51, v40
	v_mul_f32_e32 v36, v40, v36
	v_bfe_u32 v40, v36, 16, 1
	v_add3_u32 v36, v36, v40, s73
	ds_write_b16_d16_hi v210, v36 offset:7712
	ds_read_u16 v36, v210 offset:4672
	v_mul_f32_e32 v32, v33, v32
	v_mul_f32_e32 v32, v48, v32
	s_waitcnt lgkmcnt(0)
	v_lshlrev_b32_e32 v36, 16, v36
	v_mul_f32_e32 v40, 0xbfb8aa3b, v36
	v_exp_f32_e32 v40, v40
	s_nop 0
	v_add_f32_e32 v40, 1.0, v40
	v_rcp_f32_e32 v40, v40
	s_nop 0
	v_mul_f32_e32 v36, v40, v36
	v_mul_f32_e32 v36, v37, v36
	v_bfe_u32 v37, v36, 16, 1
	v_add3_u32 v36, v36, v37, s73
	ds_write_b16_d16_hi v210, v36 offset:7744
	ds_read_u16 v36, v210 offset:4704
	s_waitcnt lgkmcnt(0)
	v_lshlrev_b32_e32 v36, 16, v36
	v_mul_f32_e32 v37, 0xbfb8aa3b, v36
	v_exp_f32_e32 v37, v37
	s_nop 0
	v_add_f32_e32 v37, 1.0, v37
	v_rcp_f32_e32 v37, v37
	s_nop 0
	v_mul_f32_e32 v36, v37, v36
	v_mul_f32_e32 v32, v32, v36
	v_bfe_u32 v33, v32, 16, 1
	v_add3_u32 v32, v32, v33, s73
	ds_write_b16_d16_hi v210, v32 offset:7776
	v_mul_f32_e32 v32, v46, v46
	v_mul_f32_e32 v33, v34, v34
	v_fmac_f32_e32 v32, v42, v42
	v_fmac_f32_e32 v33, v38, v38
	v_add_f32_e32 v32, v32, v33
	ds_bpermute_b32 v33, v159, v32
	s_waitcnt lgkmcnt(0)
	v_add_f32_e32 v32, v32, v33
	ds_bpermute_b32 v33, v158, v32
	s_waitcnt lgkmcnt(0)
	v_add_f32_e32 v32, v32, v33
	ds_bpermute_b32 v33, v156, v32
	s_waitcnt lgkmcnt(0)
	v_add_f32_e32 v32, v32, v33
	ds_bpermute_b32 v33, v157, v32
	s_waitcnt lgkmcnt(0)
	v_add_f32_e32 v32, v32, v33
	ds_read_u16 v33, v211 offset:4608
	ds_read_u16 v36, v211 offset:4640
	v_fmamk_f32 v32, v32, 0x3c800000, v235
	v_rsq_f32_e32 v32, v32
	s_waitcnt lgkmcnt(1)
	v_lshlrev_b32_e32 v33, 16, v33
	v_mul_f32_e32 v37, 0xbfb8aa3b, v33
	v_exp_f32_e32 v37, v37
	s_nop 0
	v_add_f32_e32 v37, 1.0, v37
	v_rcp_f32_e32 v37, v37
	s_nop 0
	v_mul_f32_e32 v33, v37, v33
	v_mul_f32_e32 v37, v42, v32
	v_mul_f32_e32 v37, v50, v37
	v_mul_f32_e32 v33, v37, v33
	v_bfe_u32 v37, v33, 16, 1
	v_add3_u32 v33, v33, v37, s73
	ds_write_b16_d16_hi v211, v33 offset:7680
	s_waitcnt lgkmcnt(1)
	v_lshlrev_b32_e32 v33, 16, v36
	v_mul_f32_e32 v36, 0xbfb8aa3b, v33
	v_exp_f32_e32 v36, v36
	s_nop 0
	v_add_f32_e32 v36, 1.0, v36
	v_rcp_f32_e32 v36, v36
	s_nop 0
	v_mul_f32_e32 v33, v36, v33
	v_mul_f32_e32 v36, v46, v32
	v_mul_f32_e32 v36, v51, v36
	v_mul_f32_e32 v33, v36, v33
	v_bfe_u32 v36, v33, 16, 1
	v_add3_u32 v33, v33, v36, s73
	ds_write_b16_d16_hi v211, v33 offset:7712
	ds_read_u16 v33, v211 offset:4672
	s_waitcnt lgkmcnt(0)
; #define LAS __attribute__((address_space(3)))
; #define LDS_WAIT() asm volatile("s_waitcnt lgkmcnt(0)" ::: "memory")
; __device__ __forceinline__ unsigned f2bf(float f) { unsigned u = __builtin_bit_cast(unsigned, f); return (u + 0x7fffu + ((u >> 16) & 1u)) >> 16; }
; __device__ __forceinline__ float bf1(bf16 h) { return __uint_as_float(((unsigned)h) << 16); }
; __device__ __forceinline__ float sigmf(float v) { return __builtin_amdgcn_rcpf(1.0f + __builtin_amdgcn_exp2f(-1.4426950408889634f * v)); }
; __device__ __forceinline__ float siluf(float v) { return v * sigmf(v); }
; template <bool OUT> __device__ __forceinline__ void hgrn_item2(const PA& a, LAS unsigned char* lds, int layer, int bh, int c, int wave, int lane, const HRaw& raw) {
;     ...
;     __syncthreads();
;     {
;         const int rr = lane >> 3, cc = (lane & 7) * 8;
; #pragma unroll
;         for (int k = 0; k < 2; ++k) { *(LAS v4u*)(RF + (rr + 8 * k) * 72 + cc) = raw.f[k]; *(LAS v4u*)(RV + (rr + 8 * k) * 72 + cc) = raw.v[k]; if (OUT) *(LAS v4u*)(RQ + (rr + 8 * k) * 72 + cc) = raw.q[k]; }
;         LDS_WAIT();
;         const float lb = (layer == 0) ? 0.f : sigmf(a.in[4][256 + h * 64 + lane] - a.in[4][h * 64 + lane]);
;     ...
; #pragma unroll
;         for (int j = 0; j < 4; ++j) {
;             float ss = (o[0][j] * o[0][j] + o[1][j] * o[1][j]) + (o[2][j] * o[2][j] + o[3][j] * o[3][j]);
;             ss += __shfl_xor(ss, 1); ss += __shfl_xor(ss, 2); ss += __shfl_xor(ss, 4); ss += __shfl_xor(ss, 8);
;             const float rs = __builtin_amdgcn_rsqf(ss * (1.f / 64.f) + EPS);
; #pragma unroll
;             for (int nt = 0; nt < 4; ++nt) { const float gt = siluf(bf1(GT[(4 * q + j) * 72 + 16 * nt + l15]));
;                 OT[(4 * q + j) * 72 + 16 * nt + l15] = (bf16)f2bf(o[nt][j] * rs * gn[nt] * gt); }
;         }
;         LDS_WAIT();
;         { const int rr = lane >> 3, cc = (lane & 7) * 8; bf16* mp = (bf16*)(a.ws + WS_MIX) + (row0 + rr) * 1024 + h * 64 + cc;
;           *(v4u*)mp = *(const LAS v4u*)(OT + rr * 72 + cc); *(v4u*)(mp + 8 * 1024) = *(const LAS v4u*)(OT + (rr + 8) * 72 + cc); }
	v_lshlrev_b32_e32 v33, 16, v33
	v_mul_f32_e32 v36, 0xbfb8aa3b, v33
	v_exp_f32_e32 v36, v36
	s_nop 0
	v_add_f32_e32 v36, 1.0, v36
	v_rcp_f32_e32 v36, v36
	s_nop 0
	v_mul_f32_e32 v33, v36, v33
	v_mul_f32_e32 v36, v38, v32
	v_mul_f32_e32 v36, v49, v36
	v_mul_f32_e32 v33, v36, v33
	v_bfe_u32 v36, v33, 16, 1
	v_add3_u32 v33, v33, v36, s73
	ds_write_b16_d16_hi v211, v33 offset:7744
	ds_read_u16 v33, v211 offset:4704
	v_mul_f32_e32 v32, v34, v32
	v_mul_f32_e32 v32, v48, v32
	s_waitcnt lgkmcnt(0)
	v_lshlrev_b32_e32 v33, 16, v33
	v_mul_f32_e32 v36, 0xbfb8aa3b, v33
	v_exp_f32_e32 v36, v36
	s_nop 0
	v_add_f32_e32 v36, 1.0, v36
	v_rcp_f32_e32 v36, v36
	s_nop 0
	v_mul_f32_e32 v33, v36, v33
	v_mul_f32_e32 v32, v32, v33
	v_bfe_u32 v33, v32, 16, 1
	v_add3_u32 v32, v32, v33, s73
	ds_write_b16_d16_hi v211, v32 offset:7776
	v_mul_f32_e32 v32, v47, v47
	v_mul_f32_e32 v33, v35, v35
	v_fmac_f32_e32 v32, v43, v43
	v_fmac_f32_e32 v33, v39, v39
	v_add_f32_e32 v32, v32, v33
	ds_bpermute_b32 v33, v159, v32
	s_waitcnt lgkmcnt(0)
	v_add_f32_e32 v32, v32, v33
	ds_bpermute_b32 v33, v158, v32
	s_waitcnt lgkmcnt(0)
	v_add_f32_e32 v32, v32, v33
	ds_bpermute_b32 v33, v156, v32
	s_waitcnt lgkmcnt(0)
	v_add_f32_e32 v32, v32, v33
	ds_bpermute_b32 v33, v157, v32
	s_waitcnt lgkmcnt(0)
	v_add_f32_e32 v32, v32, v33
	ds_read_u16 v33, v212 offset:4608
	ds_read_u16 v34, v212 offset:4640
	v_fmamk_f32 v32, v32, 0x3c800000, v235
	v_rsq_f32_e32 v32, v32
	s_waitcnt lgkmcnt(1)
	v_lshlrev_b32_e32 v33, 16, v33
	v_mul_f32_e32 v36, 0xbfb8aa3b, v33
	v_exp_f32_e32 v36, v36
	s_nop 0
	v_add_f32_e32 v36, 1.0, v36
	v_rcp_f32_e32 v36, v36
	s_nop 0
	v_mul_f32_e32 v33, v36, v33
	v_mul_f32_e32 v36, v43, v32
	v_mul_f32_e32 v36, v50, v36
	v_mul_f32_e32 v33, v36, v33
	v_bfe_u32 v36, v33, 16, 1
	v_add3_u32 v33, v33, v36, s73
	ds_write_b16_d16_hi v212, v33 offset:7680
	s_waitcnt lgkmcnt(1)
	v_lshlrev_b32_e32 v33, 16, v34
	v_mul_f32_e32 v34, 0xbfb8aa3b, v33
	v_exp_f32_e32 v34, v34
	s_nop 0
	v_add_f32_e32 v34, 1.0, v34
	v_rcp_f32_e32 v34, v34
	s_nop 0
	v_mul_f32_e32 v33, v34, v33
	v_mul_f32_e32 v34, v47, v32
	v_mul_f32_e32 v34, v51, v34
	v_mul_f32_e32 v33, v34, v33
	v_bfe_u32 v34, v33, 16, 1
	v_add3_u32 v33, v33, v34, s73
	ds_write_b16_d16_hi v212, v33 offset:7712
	ds_read_u16 v33, v212 offset:4672
	s_waitcnt lgkmcnt(0)
	v_lshlrev_b32_e32 v33, 16, v33
	v_mul_f32_e32 v34, 0xbfb8aa3b, v33
	v_exp_f32_e32 v34, v34
	s_nop 0
	v_add_f32_e32 v34, 1.0, v34
	v_rcp_f32_e32 v34, v34
	s_nop 0
	v_mul_f32_e32 v33, v34, v33
	v_mul_f32_e32 v34, v39, v32
	v_mul_f32_e32 v34, v49, v34
	v_mul_f32_e32 v33, v34, v33
	v_bfe_u32 v34, v33, 16, 1
	v_add3_u32 v33, v33, v34, s73
	ds_write_b16_d16_hi v212, v33 offset:7744
	ds_read_u16 v33, v212 offset:4704
	v_mul_f32_e32 v32, v35, v32
	v_mul_f32_e32 v32, v48, v32
	s_waitcnt lgkmcnt(0)
	v_lshlrev_b32_e32 v33, 16, v33
	v_mul_f32_e32 v34, 0xbfb8aa3b, v33
	v_exp_f32_e32 v34, v34
	s_nop 0
	v_add_f32_e32 v34, 1.0, v34
	v_rcp_f32_e32 v34, v34
	s_nop 0
	v_mul_f32_e32 v33, v34, v33
	v_mul_f32_e32 v32, v32, v33
	v_bfe_u32 v33, v32, 16, 1
	v_add3_u32 v32, v32, v33, s73
	ds_write_b16_d16_hi v212, v32 offset:7776
	v_lshlrev_b64 v[32:33], 11, v[198:199]
	v_lshl_add_u64 v[32:33], s[90:91], 0, v[32:33]
	s_waitcnt lgkmcnt(0)
	v_lshl_add_u64 v[32:33], v[32:33], 0, s[62:63]
	v_lshl_add_u64 v[36:37], v[32:33], 0, v[220:221]
	ds_read_b128 v[32:35], v204 offset:7680
	s_waitcnt lgkmcnt(0)
	global_store_dwordx4 v[36:37], v[32:35], off
	ds_read_b128 v[32:35], v204 offset:8832
	v_add_co_u32_e32 v36, vcc, s33, v36
	s_nop 1
	v_addc_co_u32_e32 v37, vcc, 0, v37, vcc
	s_waitcnt lgkmcnt(0)
	global_store_dwordx4 v[36:37], v[32:35], off
	s_barrier
	ds_write_b128 v201, v[8:11]
	ds_write_b128 v201, v[12:15] offset:2304
	ds_write_b128 v201, v[16:19] offset:4608
	ds_write_b128 v201, v[20:23] offset:1152
	ds_write_b128 v201, v[24:27] offset:3456
	ds_write_b128 v201, v[28:31] offset:5760
	s_waitcnt lgkmcnt(0)
	v_mov_b32_e32 v8, 0
	s_and_b64 vcc, exec, s[48:49]
	v_mov_b32_e32 v19, 0
	s_cbranch_vccnz .LBB0_734
	v_lshlrev_b32_e32 v9, 5, v234
	v_add_u32_e32 v9, 0x1e000, v9
	ds_read_b32 v19, v9 offset:16
	s_waitcnt lgkmcnt(0)
